# hot loop heads (six GEMM K-loops, attention tile loop, HGRN and RWKV scan loops) aligned to 64 bytes
# speedup vs baseline: 1.0060x; 1.0060x over previous
; #define PG8_STAGE(bufoff, gbase, voff) do { _Pragma("unroll") for (int _i = 0; _i < 2; ++_i) \
;         __builtin_amdgcn_global_load_lds((const unsigned*)((const char*)(gbase) + (voff)[_i]), (LAS unsigned*)(lds + (bufoff) + ldsw + _i * 8192), 16, 0, 0); } while (0)
; #define PG8_LDA(dst, b, h) do { _Pragma("unroll") for (int m = 0; m < 4; ++m) _Pragma("unroll") for (int k = 0; k < 2; ++k) dst[m][k] = *(const LAS bf16x8*)(lds + PG8_SA(b, h) + aoff + m * 2048 + k * 1024); } while (0)
; #define PG8_LDB(dst, b, h) do { _Pragma("unroll") for (int n = 0; n < 2; ++n) _Pragma("unroll") for (int k = 0; k < 2; ++k) dst[n][k] = *(const LAS bf16x8*)(lds + PG8_SB(b, h) + boff + n * 2048 + k * 1024); } while (0)
; #define PG8_MMA(ai, bj, At, Bt) do { __builtin_amdgcn_s_setprio(1); _Pragma("unroll") for (int m = 0; m < 4; ++m) _Pragma("unroll") for (int n = 0; n < 2; ++n) _Pragma("unroll") for (int k = 0; k < 2; ++k) \
;         acc[ai][bj][m][n] = __builtin_amdgcn_mfma_f32_16x16x32_bf16(Bt[n][k], At[m][k], acc[ai][bj][m][n], 0, 0, 0); __builtin_amdgcn_s_setprio(0); } while (0)
; #define PG8_WAIT_V(n) asm volatile("s_waitcnt vmcnt(" #n ")" ::: "memory")
; #define PG8_WAIT_L(n) asm volatile("s_waitcnt lgkmcnt(" #n ")" ::: "memory")
; #define PG8_BAR __builtin_amdgcn_s_barrier()
; template <class Epi>
; __device__ __forceinline__ void gemm_phase(LAS unsigned char* lds, const Gemm g, const StaticOrder& S, const Epi& E) {
;     ...
;             const bool last = (t == nt - 2);
;             const char* a1 = cA + (size_t)(t + 1) * kstep;
;             const char* a2 = last ? nA : cA + (size_t)(t + 2) * kstep; const char* b2 = last ? nB : cB + (size_t)(t + 2) * kstep;
;             const char* a3 = a2 + kstep; const char* b3 = b2 + kstep;
;             PG8_LDB(B0, 0, 0); PG8_SCHED; PG8_LDA(At, 0, 0); PG8_STAGE(PG8_SA(1, 1), a1 + hstep, voffA);
;             PG8_WAIT_L(8); PG8_BAR; PG8_WAIT_L(0); PG8_MMA(0, 0, At, B0); PG8_BAR; PG8_SCHED;
;             PG8_LDB(B1, 0, 1); PG8_STAGE(PG8_SB(0, 0), b2, voffB);
;             PG8_BAR; PG8_WAIT_L(0); PG8_MMA(0, 1, At, B1); PG8_BAR;
;             PG8_LDA(At, 0, 1); PG8_STAGE(PG8_SA(0, 0), a2, voffA);
;             PG8_BAR; PG8_WAIT_L(0); PG8_MMA(1, 0, At, B0); PG8_BAR; PG8_SCHED;
;             PG8_STAGE(PG8_SB(0, 1), b2 + hstep, voffB);
;             PG8_WAIT_V(6); PG8_BAR; PG8_MMA(1, 1, At, B1); PG8_BAR;
.Lsp_skip_5:
	s_add_u32 s0, s22, 0xfffc0080
	s_addc_u32 s1, s23, -1
	s_add_i32 s62, 0, 0x10000
	v_add_u32_e32 v142, s62, v161
	ds_read_b128 v[122:125], v142
	ds_read_b128 v[126:129], v142 offset:1024
	ds_read_b128 v[138:141], v142 offset:2048
	ds_read_b128 v[142:145], v142 offset:3072
	s_cmp_eq_u32 s61, 12
	s_cselect_b32 s27, s15, s1
	s_cselect_b32 s26, s57, s0
	s_cselect_b32 s25, s13, s60
	s_cselect_b32 s24, s58, s59
	v_lshl_add_u64 v[186:187], s[22:23], 0, v[152:153]
	s_add_i32 m0, s21, 0xc000
	ds_read_b128 v[166:169], v165
	ds_read_b128 v[170:173], v165 offset:1024
	ds_read_b128 v[174:177], v165 offset:2048
	ds_read_b128 v[190:193], v165 offset:3072
	ds_read_b128 v[194:197], v165 offset:4096
	ds_read_b128 v[198:201], v165 offset:5120
	ds_read_b128 v[202:205], v165 offset:6144
	ds_read_b128 v[206:209], v165 offset:7168
	global_load_lds_dwordx4 v[186:187], off
	s_add_i32 m0, s21, 0xe000
	v_lshl_add_u64 v[186:187], s[22:23], 0, v[154:155]
	global_load_lds_dwordx4 v[186:187], off
	s_waitcnt lgkmcnt(8)
	s_barrier
	s_waitcnt lgkmcnt(0)
	v_mfma_f32_16x16x32_bf16 v[134:137], v[122:125], v[166:169], 0
	v_mfma_f32_16x16x32_bf16 v[130:133], v[138:141], v[166:169], 0
	v_mfma_f32_16x16x32_bf16 v[118:121], v[122:125], v[174:177], 0
	v_mfma_f32_16x16x32_bf16 v[114:117], v[138:141], v[174:177], 0
	v_mfma_f32_16x16x32_bf16 v[110:113], v[122:125], v[194:197], 0
	v_mfma_f32_16x16x32_bf16 v[106:109], v[138:141], v[194:197], 0
	v_mfma_f32_16x16x32_bf16 v[102:105], v[122:125], v[202:205], 0
	v_mfma_f32_16x16x32_bf16 v[98:101], v[138:141], v[202:205], 0
	v_mfma_f32_16x16x32_bf16 v[134:137], v[126:129], v[170:173], v[134:137]
	v_mfma_f32_16x16x32_bf16 v[130:133], v[142:145], v[170:173], v[130:133]
	v_mfma_f32_16x16x32_bf16 v[118:121], v[126:129], v[190:193], v[118:121]
	v_mfma_f32_16x16x32_bf16 v[114:117], v[142:145], v[190:193], v[114:117]
	v_mfma_f32_16x16x32_bf16 v[110:113], v[126:129], v[198:201], v[110:113]
	v_mfma_f32_16x16x32_bf16 v[106:109], v[142:145], v[198:201], v[106:109]
	v_mfma_f32_16x16x32_bf16 v[102:105], v[126:129], v[206:209], v[102:105]
	v_mfma_f32_16x16x32_bf16 v[98:101], v[142:145], v[206:209], v[98:101]
	s_barrier
	s_add_i32 s0, 0, 0x14000
	s_add_i32 s1, s62, s36
	v_add_u32_e32 v158, s0, v161
	v_lshl_add_u64 v[186:187], s[24:25], 0, v[4:5]
	s_mov_b32 m0, s1
	ds_read_b128 v[210:213], v158
	ds_read_b128 v[214:217], v158 offset:1024
	ds_read_b128 v[218:221], v158 offset:2048
	ds_read_b128 v[222:225], v158 offset:3072
	global_load_lds_dwordx4 v[186:187], off
	s_add_i32 m0, s1, 0x2000
	v_lshl_add_u64 v[226:227], s[24:25], 0, v[146:147]
	global_load_lds_dwordx4 v[226:227], off
	s_barrier
	s_waitcnt lgkmcnt(0)
	v_mfma_f32_16x16x32_bf16 v[70:73], v[210:213], v[166:169], 0
	v_mfma_f32_16x16x32_bf16 v[66:69], v[218:221], v[166:169], 0
	v_mfma_f32_16x16x32_bf16 v[54:57], v[210:213], v[174:177], 0
	v_mfma_f32_16x16x32_bf16 v[50:53], v[218:221], v[174:177], 0
	v_mfma_f32_16x16x32_bf16 v[46:49], v[210:213], v[194:197], 0
	v_mfma_f32_16x16x32_bf16 v[42:45], v[218:221], v[194:197], 0
	v_mfma_f32_16x16x32_bf16 v[38:41], v[210:213], v[202:205], 0
	v_mfma_f32_16x16x32_bf16 v[34:37], v[218:221], v[202:205], 0
	v_mfma_f32_16x16x32_bf16 v[70:73], v[214:217], v[170:173], v[70:73]
	v_mfma_f32_16x16x32_bf16 v[66:69], v[222:225], v[170:173], v[66:69]
	v_mfma_f32_16x16x32_bf16 v[54:57], v[214:217], v[190:193], v[54:57]
	v_mfma_f32_16x16x32_bf16 v[50:53], v[222:225], v[190:193], v[50:53]
	v_mfma_f32_16x16x32_bf16 v[46:49], v[214:217], v[198:201], v[46:49]
	v_mfma_f32_16x16x32_bf16 v[42:45], v[222:225], v[198:201], v[42:45]
	v_mfma_f32_16x16x32_bf16 v[38:41], v[214:217], v[206:209], v[38:41]
	v_mfma_f32_16x16x32_bf16 v[34:37], v[222:225], v[206:209], v[34:37]
	s_mov_b32 m0, s21
	v_lshl_add_u64 v[242:243], s[26:27], 0, v[150:151]
	s_barrier
	ds_read_b128 v[166:169], v165 offset:16384
	ds_read_b128 v[170:173], v165 offset:17408
	ds_read_b128 v[174:177], v165 offset:18432
	ds_read_b128 v[190:193], v165 offset:19456
	ds_read_b128 v[194:197], v165 offset:20480
	ds_read_b128 v[198:201], v165 offset:21504
	ds_read_b128 v[202:205], v165 offset:22528
	ds_read_b128 v[206:209], v165 offset:23552
	global_load_lds_dwordx4 v[242:243], off
	s_mov_b32 m0, s42
	v_lshl_add_u64 v[244:245], s[26:27], 0, v[148:149]
	global_load_lds_dwordx4 v[244:245], off
	s_barrier
	s_waitcnt lgkmcnt(0)
	v_mfma_f32_16x16x32_bf16 v[94:97], v[122:125], v[166:169], 0
	v_mfma_f32_16x16x32_bf16 v[90:93], v[138:141], v[166:169], 0
	v_mfma_f32_16x16x32_bf16 v[86:89], v[122:125], v[174:177], 0
	v_mfma_f32_16x16x32_bf16 v[82:85], v[138:141], v[174:177], 0
	v_mfma_f32_16x16x32_bf16 v[78:81], v[122:125], v[194:197], 0
	v_mfma_f32_16x16x32_bf16 v[74:77], v[138:141], v[194:197], 0
	v_mfma_f32_16x16x32_bf16 v[62:65], v[122:125], v[202:205], 0
	v_mfma_f32_16x16x32_bf16 v[58:61], v[138:141], v[202:205], 0
	v_mfma_f32_16x16x32_bf16 v[94:97], v[126:129], v[170:173], v[94:97]
	v_mfma_f32_16x16x32_bf16 v[90:93], v[142:145], v[170:173], v[90:93]
	v_mfma_f32_16x16x32_bf16 v[86:89], v[126:129], v[190:193], v[86:89]
	v_mfma_f32_16x16x32_bf16 v[82:85], v[142:145], v[190:193], v[82:85]
	v_mfma_f32_16x16x32_bf16 v[78:81], v[126:129], v[198:201], v[78:81]
	v_mfma_f32_16x16x32_bf16 v[74:77], v[142:145], v[198:201], v[74:77]
	v_mfma_f32_16x16x32_bf16 v[62:65], v[126:129], v[206:209], v[62:65]
	v_mfma_f32_16x16x32_bf16 v[58:61], v[142:145], v[206:209], v[58:61]
	s_barrier
	s_add_u32 s62, s24, 0x40000
	s_addc_u32 s63, s25, 0
	s_add_i32 s0, s0, s36
	s_mov_b32 m0, s0
	v_lshl_add_u64 v[122:123], s[62:63], 0, v[4:5]
	global_load_lds_dwordx4 v[122:123], off
	s_add_i32 m0, s0, 0x2000
	v_lshl_add_u64 v[122:123], s[62:63], 0, v[146:147]
	global_load_lds_dwordx4 v[122:123], off
	s_waitcnt vmcnt(6)
	s_barrier
; #define PG8_STAGE(bufoff, gbase, voff) do { _Pragma("unroll") for (int _i = 0; _i < 2; ++_i) \
;         __builtin_amdgcn_global_load_lds((const unsigned*)((const char*)(gbase) + (voff)[_i]), (LAS unsigned*)(lds + (bufoff) + ldsw + _i * 8192), 16, 0, 0); } while (0)
; #define PG8_LDA(dst, b, h) do { _Pragma("unroll") for (int m = 0; m < 4; ++m) _Pragma("unroll") for (int k = 0; k < 2; ++k) dst[m][k] = *(const LAS bf16x8*)(lds + PG8_SA(b, h) + aoff + m * 2048 + k * 1024); } while (0)
; #define PG8_LDB(dst, b, h) do { _Pragma("unroll") for (int n = 0; n < 2; ++n) _Pragma("unroll") for (int k = 0; k < 2; ++k) dst[n][k] = *(const LAS bf16x8*)(lds + PG8_SB(b, h) + boff + n * 2048 + k * 1024); } while (0)
; #define PG8_MMA(ai, bj, At, Bt) do { __builtin_amdgcn_s_setprio(1); _Pragma("unroll") for (int m = 0; m < 4; ++m) _Pragma("unroll") for (int n = 0; n < 2; ++n) _Pragma("unroll") for (int k = 0; k < 2; ++k) \
;         acc[ai][bj][m][n] = __builtin_amdgcn_mfma_f32_16x16x32_bf16(Bt[n][k], At[m][k], acc[ai][bj][m][n], 0, 0, 0); __builtin_amdgcn_s_setprio(0); } while (0)
; #define PG8_WAIT_V(n) asm volatile("s_waitcnt vmcnt(" #n ")" ::: "memory")
; #define PG8_WAIT_L(n) asm volatile("s_waitcnt lgkmcnt(" #n ")" ::: "memory")
; #define PG8_BAR __builtin_amdgcn_s_barrier()
; #define PG8_SCHED __builtin_amdgcn_sched_barrier(0)
; template <class Epi>
; __device__ __forceinline__ void gemm_phase(LAS unsigned char* lds, const Gemm g, const StaticOrder& S, const Epi& E) {
;     ...
;             PG8_WAIT_V(6); PG8_BAR; PG8_MMA(1, 1, At, B1); PG8_BAR;
;             PG8_LDB(B0, 1, 0); PG8_SCHED; PG8_LDA(At, 1, 0); PG8_STAGE(PG8_SA(0, 1), a2 + hstep, voffA);
;             PG8_WAIT_L(8); PG8_BAR; PG8_WAIT_L(0); PG8_MMA(0, 0, At, B0); PG8_BAR; PG8_SCHED;
;             PG8_LDB(B1, 1, 1); PG8_STAGE(PG8_SB(1, 0), b3, voffB);
;             PG8_BAR; PG8_WAIT_L(0); PG8_MMA(0, 1, At, B1); PG8_BAR;
	v_mfma_f32_16x16x32_bf16 v[30:33], v[210:213], v[166:169], 0
	v_mfma_f32_16x16x32_bf16 v[26:29], v[218:221], v[166:169], 0
	v_mfma_f32_16x16x32_bf16 v[22:25], v[210:213], v[174:177], 0
	v_mfma_f32_16x16x32_bf16 v[18:21], v[218:221], v[174:177], 0
	v_mfma_f32_16x16x32_bf16 v[14:17], v[210:213], v[194:197], 0
	v_mfma_f32_16x16x32_bf16 v[10:13], v[218:221], v[194:197], 0
	v_mfma_f32_16x16x32_bf16 v[6:9], v[210:213], v[202:205], 0
	v_mfma_f32_16x16x32_bf16 v[0:3], v[218:221], v[202:205], 0
	v_mfma_f32_16x16x32_bf16 v[30:33], v[214:217], v[170:173], v[30:33]
	v_mfma_f32_16x16x32_bf16 v[26:29], v[222:225], v[170:173], v[26:29]
	v_mfma_f32_16x16x32_bf16 v[22:25], v[214:217], v[190:193], v[22:25]
	v_mfma_f32_16x16x32_bf16 v[18:21], v[222:225], v[190:193], v[18:21]
	v_mfma_f32_16x16x32_bf16 v[14:17], v[214:217], v[198:201], v[14:17]
	v_mfma_f32_16x16x32_bf16 v[10:13], v[222:225], v[198:201], v[10:13]
	v_mfma_f32_16x16x32_bf16 v[6:9], v[214:217], v[206:209], v[6:9]
	v_mfma_f32_16x16x32_bf16 v[0:3], v[222:225], v[206:209], v[0:3]
	s_add_i32 s0, 0, 0x18000
	v_add_u32_e32 v142, s0, v161
	s_barrier
	ds_read_b128 v[122:125], v142
	ds_read_b128 v[126:129], v142 offset:1024
	ds_read_b128 v[138:141], v142 offset:2048
	ds_read_b128 v[142:145], v142 offset:3072
	s_add_u32 s26, s26, 0x40000
	s_addc_u32 s27, s27, 0
	s_mov_b32 m0, s43
	v_lshl_add_u64 v[210:211], s[26:27], 0, v[150:151]
	ds_read_b128 v[166:169], v165 offset:32768
	ds_read_b128 v[170:173], v165 offset:33792
	ds_read_b128 v[174:177], v165 offset:34816
	ds_read_b128 v[190:193], v165 offset:35840
	ds_read_b128 v[194:197], v165 offset:36864
	ds_read_b128 v[198:201], v165 offset:37888
	ds_read_b128 v[202:205], v165 offset:38912
	ds_read_b128 v[206:209], v165 offset:39936
	global_load_lds_dwordx4 v[210:211], off
	s_mov_b32 m0, s48
	v_lshl_add_u64 v[210:211], s[26:27], 0, v[148:149]
	global_load_lds_dwordx4 v[210:211], off
	s_waitcnt lgkmcnt(8)
	s_barrier
	s_waitcnt lgkmcnt(0)
	v_mfma_f32_16x16x32_bf16 v[134:137], v[122:125], v[166:169], v[134:137]
	v_mfma_f32_16x16x32_bf16 v[130:133], v[138:141], v[166:169], v[130:133]
	v_mfma_f32_16x16x32_bf16 v[118:121], v[122:125], v[174:177], v[118:121]
	v_mfma_f32_16x16x32_bf16 v[114:117], v[138:141], v[174:177], v[114:117]
	v_mfma_f32_16x16x32_bf16 v[110:113], v[122:125], v[194:197], v[110:113]
	v_mfma_f32_16x16x32_bf16 v[106:109], v[138:141], v[194:197], v[106:109]
	v_mfma_f32_16x16x32_bf16 v[102:105], v[122:125], v[202:205], v[102:105]
	v_mfma_f32_16x16x32_bf16 v[98:101], v[138:141], v[202:205], v[98:101]
	v_mfma_f32_16x16x32_bf16 v[134:137], v[126:129], v[170:173], v[134:137]
	v_mfma_f32_16x16x32_bf16 v[130:133], v[142:145], v[170:173], v[130:133]
	v_mfma_f32_16x16x32_bf16 v[118:121], v[126:129], v[190:193], v[118:121]
	v_mfma_f32_16x16x32_bf16 v[114:117], v[142:145], v[190:193], v[114:117]
	v_mfma_f32_16x16x32_bf16 v[110:113], v[126:129], v[198:201], v[110:113]
	v_mfma_f32_16x16x32_bf16 v[106:109], v[142:145], v[198:201], v[106:109]
	v_mfma_f32_16x16x32_bf16 v[102:105], v[126:129], v[206:209], v[102:105]
	v_mfma_f32_16x16x32_bf16 v[98:101], v[142:145], v[206:209], v[98:101]
	s_barrier
	s_add_i32 s1, 0, 0x1c000
	s_add_i32 s0, s0, s36
	v_add_u32_e32 v158, s1, v161
	v_lshl_add_u64 v[186:187], v[186:187], 0, s[86:87]
	s_mov_b32 m0, s0
	ds_read_b128 v[210:213], v158
	ds_read_b128 v[214:217], v158 offset:1024
	ds_read_b128 v[218:221], v158 offset:2048
	ds_read_b128 v[222:225], v158 offset:3072
	global_load_lds_dwordx4 v[186:187], off
	s_add_i32 m0, s0, 0x2000
	v_lshl_add_u64 v[186:187], v[226:227], 0, s[86:87]
	global_load_lds_dwordx4 v[186:187], off
	s_barrier
; #define PG8_STAGE(bufoff, gbase, voff) do { _Pragma("unroll") for (int _i = 0; _i < 2; ++_i) \
;         __builtin_amdgcn_global_load_lds((const unsigned*)((const char*)(gbase) + (voff)[_i]), (LAS unsigned*)(lds + (bufoff) + ldsw + _i * 8192), 16, 0, 0); } while (0)
; #define PG8_LDA(dst, b, h) do { _Pragma("unroll") for (int m = 0; m < 4; ++m) _Pragma("unroll") for (int k = 0; k < 2; ++k) dst[m][k] = *(const LAS bf16x8*)(lds + PG8_SA(b, h) + aoff + m * 2048 + k * 1024); } while (0)
; #define PG8_MMA(ai, bj, At, Bt) do { __builtin_amdgcn_s_setprio(1); _Pragma("unroll") for (int m = 0; m < 4; ++m) _Pragma("unroll") for (int n = 0; n < 2; ++n) _Pragma("unroll") for (int k = 0; k < 2; ++k) \
;         acc[ai][bj][m][n] = __builtin_amdgcn_mfma_f32_16x16x32_bf16(Bt[n][k], At[m][k], acc[ai][bj][m][n], 0, 0, 0); __builtin_amdgcn_s_setprio(0); } while (0)
; #define PG8_WAIT_V(n) asm volatile("s_waitcnt vmcnt(" #n ")" ::: "memory")
; #define PG8_WAIT_L(n) asm volatile("s_waitcnt lgkmcnt(" #n ")" ::: "memory")
; #define PG8_BAR __builtin_amdgcn_s_barrier()
; #define PG8_SCHED __builtin_amdgcn_sched_barrier(0)
; template <class Epi>
; __device__ __forceinline__ void gemm_phase(LAS unsigned char* lds, const Gemm g, const StaticOrder& S, const Epi& E) {
;     ...
;             PG8_BAR; PG8_WAIT_L(0); PG8_MMA(0, 1, At, B1); PG8_BAR;
;             PG8_LDA(At, 1, 1); PG8_STAGE(PG8_SA(1, 0), a3, voffA);
;             PG8_BAR; PG8_WAIT_L(0); PG8_MMA(1, 0, At, B0); PG8_BAR; PG8_SCHED;
;             PG8_STAGE(PG8_SB(1, 1), b3 + hstep, voffB);
;             PG8_WAIT_V(6); PG8_BAR; PG8_MMA(1, 1, At, B1); PG8_BAR;
;         }
	s_waitcnt lgkmcnt(0)
	v_mfma_f32_16x16x32_bf16 v[70:73], v[210:213], v[166:169], v[70:73]
	v_mfma_f32_16x16x32_bf16 v[66:69], v[218:221], v[166:169], v[66:69]
	v_mfma_f32_16x16x32_bf16 v[54:57], v[210:213], v[174:177], v[54:57]
	v_mfma_f32_16x16x32_bf16 v[50:53], v[218:221], v[174:177], v[50:53]
	v_mfma_f32_16x16x32_bf16 v[46:49], v[210:213], v[194:197], v[46:49]
	v_mfma_f32_16x16x32_bf16 v[42:45], v[218:221], v[194:197], v[42:45]
	v_mfma_f32_16x16x32_bf16 v[38:41], v[210:213], v[202:205], v[38:41]
	v_mfma_f32_16x16x32_bf16 v[34:37], v[218:221], v[202:205], v[34:37]
	v_mfma_f32_16x16x32_bf16 v[70:73], v[214:217], v[170:173], v[70:73]
	v_mfma_f32_16x16x32_bf16 v[66:69], v[222:225], v[170:173], v[66:69]
	v_mfma_f32_16x16x32_bf16 v[54:57], v[214:217], v[190:193], v[54:57]
	v_mfma_f32_16x16x32_bf16 v[50:53], v[222:225], v[190:193], v[50:53]
	v_mfma_f32_16x16x32_bf16 v[46:49], v[214:217], v[198:201], v[46:49]
	v_mfma_f32_16x16x32_bf16 v[42:45], v[222:225], v[198:201], v[42:45]
	v_mfma_f32_16x16x32_bf16 v[38:41], v[214:217], v[206:209], v[38:41]
	v_mfma_f32_16x16x32_bf16 v[34:37], v[222:225], v[206:209], v[34:37]
	s_mov_b32 m0, s51
	v_lshl_add_u64 v[186:187], v[242:243], 0, s[86:87]
	s_barrier
	ds_read_b128 v[166:169], v165 offset:49152
	ds_read_b128 v[170:173], v165 offset:50176
	ds_read_b128 v[174:177], v165 offset:51200
	ds_read_b128 v[190:193], v165 offset:52224
	ds_read_b128 v[194:197], v165 offset:53248
	ds_read_b128 v[198:201], v165 offset:54272
	ds_read_b128 v[202:205], v165 offset:55296
	ds_read_b128 v[206:209], v165 offset:56320
	global_load_lds_dwordx4 v[186:187], off
	s_mov_b32 m0, s54
	v_lshl_add_u64 v[186:187], v[244:245], 0, s[86:87]
	global_load_lds_dwordx4 v[186:187], off
	s_barrier
	s_waitcnt lgkmcnt(0)
	v_mfma_f32_16x16x32_bf16 v[94:97], v[122:125], v[166:169], v[94:97]
	v_mfma_f32_16x16x32_bf16 v[90:93], v[138:141], v[166:169], v[90:93]
	v_mfma_f32_16x16x32_bf16 v[86:89], v[122:125], v[174:177], v[86:89]
	v_mfma_f32_16x16x32_bf16 v[82:85], v[138:141], v[174:177], v[82:85]
	v_mfma_f32_16x16x32_bf16 v[78:81], v[122:125], v[194:197], v[78:81]
	v_mfma_f32_16x16x32_bf16 v[74:77], v[138:141], v[194:197], v[74:77]
	v_mfma_f32_16x16x32_bf16 v[62:65], v[122:125], v[202:205], v[62:65]
	v_mfma_f32_16x16x32_bf16 v[58:61], v[138:141], v[202:205], v[58:61]
	v_mfma_f32_16x16x32_bf16 v[94:97], v[126:129], v[170:173], v[94:97]
	v_mfma_f32_16x16x32_bf16 v[90:93], v[142:145], v[170:173], v[90:93]
	v_mfma_f32_16x16x32_bf16 v[86:89], v[126:129], v[190:193], v[86:89]
	v_mfma_f32_16x16x32_bf16 v[82:85], v[142:145], v[190:193], v[82:85]
	v_mfma_f32_16x16x32_bf16 v[78:81], v[126:129], v[198:201], v[78:81]
	v_mfma_f32_16x16x32_bf16 v[74:77], v[142:145], v[198:201], v[74:77]
	v_mfma_f32_16x16x32_bf16 v[62:65], v[126:129], v[206:209], v[62:65]
	v_mfma_f32_16x16x32_bf16 v[58:61], v[142:145], v[206:209], v[58:61]
	s_barrier
	s_add_u32 s24, s24, 0x40080
	s_addc_u32 s25, s25, 0
	s_add_i32 s0, s1, s36
	s_mov_b32 m0, s0
	v_lshl_add_u64 v[122:123], s[24:25], 0, v[4:5]
	global_load_lds_dwordx4 v[122:123], off
	s_add_i32 m0, s0, 0x2000
	v_lshl_add_u64 v[122:123], s[24:25], 0, v[146:147]
	global_load_lds_dwordx4 v[122:123], off
	s_waitcnt vmcnt(6)
	s_barrier
	v_mfma_f32_16x16x32_bf16 v[30:33], v[210:213], v[166:169], v[30:33]
	v_mfma_f32_16x16x32_bf16 v[26:29], v[218:221], v[166:169], v[26:29]
	v_mfma_f32_16x16x32_bf16 v[22:25], v[210:213], v[174:177], v[22:25]
	v_mfma_f32_16x16x32_bf16 v[18:21], v[218:221], v[174:177], v[18:21]
	v_mfma_f32_16x16x32_bf16 v[14:17], v[210:213], v[194:197], v[14:17]
	v_mfma_f32_16x16x32_bf16 v[10:13], v[218:221], v[194:197], v[10:13]
	v_mfma_f32_16x16x32_bf16 v[6:9], v[210:213], v[202:205], v[6:9]
	v_mfma_f32_16x16x32_bf16 v[0:3], v[218:221], v[202:205], v[0:3]
	v_mfma_f32_16x16x32_bf16 v[30:33], v[214:217], v[170:173], v[30:33]
	v_mfma_f32_16x16x32_bf16 v[26:29], v[222:225], v[170:173], v[26:29]
	v_mfma_f32_16x16x32_bf16 v[22:25], v[214:217], v[190:193], v[22:25]
	v_mfma_f32_16x16x32_bf16 v[18:21], v[222:225], v[190:193], v[18:21]
	v_mfma_f32_16x16x32_bf16 v[14:17], v[214:217], v[198:201], v[14:17]
	v_mfma_f32_16x16x32_bf16 v[10:13], v[222:225], v[198:201], v[10:13]
	v_mfma_f32_16x16x32_bf16 v[6:9], v[214:217], v[206:209], v[6:9]
	v_mfma_f32_16x16x32_bf16 v[0:3], v[222:225], v[206:209], v[0:3]
	s_add_i32 s61, s61, 2
	s_add_u32 s22, s22, 0x100
	s_addc_u32 s23, s23, 0
	s_add_u32 s59, s59, 0x100
	s_addc_u32 s60, s60, 0
	s_cmp_gt_u32 s61, 13
	s_barrier
	s_cbranch_scc1 .Lpeel_exit_5
	.p2align 6

; #define HG_LD(X, tl_) do { const float* f_ = sF + (tl_) * 128 + seg * 4; const float* q_ = sQ + (tl_) * 128 + seg * 4;   \
;                 X##f0 = *(const f32x4*)(f_); X##f1 = *(const f32x4*)(f_ + 64); X##q0 = *(const f32x4*)(q_); X##q1 = *(const f32x4*)(q_ + 64); \
;                 X##va = sDV[(tl_) * 64 + cp]; X##vb = sDV[(tl_) * 64 + 32 + cp]; } while (0)
; __device__ __forceinline__ void phase_hgrn(KP P, int l_, unsigned char* shm) {
;     ...
;                 for (int tl = 0; tl < T; tl += 2) {
;                     HG_LD(B, tl + 1);
;                     HG_STEP(A, tl);
;                     HG_LD(A, tl + 2);
;                     HG_STEP(B, tl + 1);
;                 }
.LBB0_2163:
	s_add_i32 s17, s17, 4
	v_add_u32_e32 v135, 0x1000, v135
	v_add_u32_e32 v136, 0x1000, v136
	v_add_u32_e32 v130, 0x400, v130
	s_cmp_gt_u32 s17, 29
	v_add_u32_e32 v129, 0x800, v129
	s_cbranch_scc1 .LBB0_2172
	.p2align 6

; #define PG8_STAGE(bufoff, gbase, voff) do { _Pragma("unroll") for (int _i = 0; _i < 2; ++_i) \
;         __builtin_amdgcn_global_load_lds((const unsigned*)((const char*)(gbase) + (voff)[_i]), (LAS unsigned*)(lds + (bufoff) + ldsw + _i * 8192), 16, 0, 0); } while (0)
; #define PG8_LDA(dst, b, h) do { _Pragma("unroll") for (int m = 0; m < 4; ++m) _Pragma("unroll") for (int k = 0; k < 2; ++k) dst[m][k] = *(const LAS bf16x8*)(lds + PG8_SA(b, h) + aoff + m * 2048 + k * 1024); } while (0)
; #define PG8_LDB(dst, b, h) do { _Pragma("unroll") for (int n = 0; n < 2; ++n) _Pragma("unroll") for (int k = 0; k < 2; ++k) dst[n][k] = *(const LAS bf16x8*)(lds + PG8_SB(b, h) + boff + n * 2048 + k * 1024); } while (0)
; #define PG8_MMA(ai, bj, At, Bt) do { __builtin_amdgcn_s_setprio(1); _Pragma("unroll") for (int m = 0; m < 4; ++m) _Pragma("unroll") for (int n = 0; n < 2; ++n) _Pragma("unroll") for (int k = 0; k < 2; ++k) \
;         acc[ai][bj][m][n] = __builtin_amdgcn_mfma_f32_16x16x32_bf16(Bt[n][k], At[m][k], acc[ai][bj][m][n], 0, 0, 0); __builtin_amdgcn_s_setprio(0); } while (0)
; #define PG8_WAIT_V(n) asm volatile("s_waitcnt vmcnt(" #n ")" ::: "memory")
; #define PG8_WAIT_L(n) asm volatile("s_waitcnt lgkmcnt(" #n ")" ::: "memory")
; #define PG8_BAR __builtin_amdgcn_s_barrier()
; template <class Epi>
; __device__ __forceinline__ void gemm_phase(LAS unsigned char* lds, const Gemm g, const StaticOrder& S, const Epi& E) {
;     ...
;             const bool last = (t == nt - 2);
;             const char* a1 = cA + (size_t)(t + 1) * kstep;
;             const char* a2 = last ? nA : cA + (size_t)(t + 2) * kstep; const char* b2 = last ? nB : cB + (size_t)(t + 2) * kstep;
;             const char* a3 = a2 + kstep; const char* b3 = b2 + kstep;
;             PG8_LDB(B0, 0, 0); PG8_SCHED; PG8_LDA(At, 0, 0); PG8_STAGE(PG8_SA(1, 1), a1 + hstep, voffA);
;             PG8_WAIT_L(8); PG8_BAR; PG8_WAIT_L(0); PG8_MMA(0, 0, At, B0); PG8_BAR; PG8_SCHED;
;             PG8_LDB(B1, 0, 1); PG8_STAGE(PG8_SB(0, 0), b2, voffB);
;             PG8_BAR; PG8_WAIT_L(0); PG8_MMA(0, 1, At, B1); PG8_BAR;
;             PG8_LDA(At, 0, 1); PG8_STAGE(PG8_SA(0, 0), a2, voffA);
;             PG8_BAR; PG8_WAIT_L(0); PG8_MMA(1, 0, At, B0); PG8_BAR; PG8_SCHED;
;             PG8_STAGE(PG8_SB(0, 1), b2 + hstep, voffB);
;             PG8_WAIT_V(6); PG8_BAR; PG8_MMA(1, 1, At, B1); PG8_BAR;
.Lsp_skip_4:
	s_add_u32 s14, s12, 0x100
	s_addc_u32 s15, s13, 0
	s_add_i32 s0, 0, 0x10000
	v_add_u32_e32 v156, s0, v141
	ds_read_b128 v[144:147], v156
	ds_read_b128 v[148:151], v156 offset:1024
	ds_read_b128 v[152:155], v156 offset:2048
	ds_read_b128 v[156:159], v156 offset:3072
	s_cmp_eq_u32 s41, 2
	s_cselect_b32 s19, s7, s15
	s_cselect_b32 s18, s6, s14
	s_cselect_b32 s17, s9, s40
	s_cselect_b32 s16, s8, s39
	v_lshl_add_u64 v[176:177], s[12:13], 0, v[136:137]
	s_add_i32 m0, s26, 0xc000
	ds_read_b128 v[160:163], v143
	ds_read_b128 v[164:167], v143 offset:1024
	ds_read_b128 v[168:171], v143 offset:2048
	ds_read_b128 v[172:175], v143 offset:3072
	ds_read_b128 v[190:193], v143 offset:4096
	ds_read_b128 v[194:197], v143 offset:5120
	ds_read_b128 v[198:201], v143 offset:6144
	ds_read_b128 v[202:205], v143 offset:7168
	global_load_lds_dwordx4 v[176:177], off
	s_add_i32 m0, s26, 0xe000
	v_lshl_add_u64 v[176:177], s[12:13], 0, v[138:139]
	global_load_lds_dwordx4 v[176:177], off
	s_waitcnt lgkmcnt(8)
	s_barrier
	s_waitcnt lgkmcnt(0)
	v_mfma_f32_16x16x32_bf16 v[126:129], v[144:147], v[160:163], 0
	v_mfma_f32_16x16x32_bf16 v[122:125], v[152:155], v[160:163], 0
	v_mfma_f32_16x16x32_bf16 v[118:121], v[144:147], v[168:171], 0
	v_mfma_f32_16x16x32_bf16 v[114:117], v[152:155], v[168:171], 0
	v_mfma_f32_16x16x32_bf16 v[110:113], v[144:147], v[190:193], 0
	v_mfma_f32_16x16x32_bf16 v[106:109], v[152:155], v[190:193], 0
	v_mfma_f32_16x16x32_bf16 v[102:105], v[144:147], v[198:201], 0
	v_mfma_f32_16x16x32_bf16 v[98:101], v[152:155], v[198:201], 0
	v_mfma_f32_16x16x32_bf16 v[126:129], v[148:151], v[164:167], v[126:129]
	v_mfma_f32_16x16x32_bf16 v[122:125], v[156:159], v[164:167], v[122:125]
	v_mfma_f32_16x16x32_bf16 v[118:121], v[148:151], v[172:175], v[118:121]
	v_mfma_f32_16x16x32_bf16 v[114:117], v[156:159], v[172:175], v[114:117]
	v_mfma_f32_16x16x32_bf16 v[110:113], v[148:151], v[194:197], v[110:113]
	v_mfma_f32_16x16x32_bf16 v[106:109], v[156:159], v[194:197], v[106:109]
	v_mfma_f32_16x16x32_bf16 v[102:105], v[148:151], v[202:205], v[102:105]
	v_mfma_f32_16x16x32_bf16 v[98:101], v[156:159], v[202:205], v[98:101]
	s_barrier
	s_add_i32 s1, 0, 0x14000
	v_add_u32_e32 v176, s1, v141
	s_add_i32 s0, s0, s25
	ds_read_b128 v[206:209], v176
	ds_read_b128 v[210:213], v176 offset:1024
	ds_read_b128 v[214:217], v176 offset:2048
	ds_read_b128 v[218:221], v176 offset:3072
	v_lshl_add_u64 v[176:177], s[16:17], 0, v[4:5]
	s_mov_b32 m0, s0
	v_lshl_add_u64 v[186:187], s[16:17], 0, v[130:131]
	global_load_lds_dwordx4 v[176:177], off
	s_add_i32 m0, s0, 0x2000
	s_nop 0
	global_load_lds_dwordx4 v[186:187], off
	s_barrier
	s_waitcnt lgkmcnt(0)
	v_mfma_f32_16x16x32_bf16 v[74:77], v[206:209], v[160:163], 0
	v_mfma_f32_16x16x32_bf16 v[66:69], v[214:217], v[160:163], 0
	v_mfma_f32_16x16x32_bf16 v[58:61], v[206:209], v[168:171], 0
	v_mfma_f32_16x16x32_bf16 v[50:53], v[214:217], v[168:171], 0
	v_mfma_f32_16x16x32_bf16 v[46:49], v[206:209], v[190:193], 0
	v_mfma_f32_16x16x32_bf16 v[42:45], v[214:217], v[190:193], 0
	v_mfma_f32_16x16x32_bf16 v[38:41], v[206:209], v[198:201], 0
	v_mfma_f32_16x16x32_bf16 v[34:37], v[214:217], v[198:201], 0
	v_mfma_f32_16x16x32_bf16 v[74:77], v[210:213], v[164:167], v[74:77]
	v_mfma_f32_16x16x32_bf16 v[66:69], v[218:221], v[164:167], v[66:69]
	v_mfma_f32_16x16x32_bf16 v[58:61], v[210:213], v[172:175], v[58:61]
	v_mfma_f32_16x16x32_bf16 v[50:53], v[218:221], v[172:175], v[50:53]
	v_mfma_f32_16x16x32_bf16 v[46:49], v[210:213], v[194:197], v[46:49]
	v_mfma_f32_16x16x32_bf16 v[42:45], v[218:221], v[194:197], v[42:45]
	v_mfma_f32_16x16x32_bf16 v[38:41], v[210:213], v[202:205], v[38:41]
	v_mfma_f32_16x16x32_bf16 v[34:37], v[218:221], v[202:205], v[34:37]
	s_mov_b32 m0, s26
	v_lshl_add_u64 v[222:223], s[18:19], 0, v[134:135]
	s_barrier
	ds_read_b128 v[160:163], v143 offset:16384
	ds_read_b128 v[164:167], v143 offset:17408
	ds_read_b128 v[168:171], v143 offset:18432
	ds_read_b128 v[172:175], v143 offset:19456
	ds_read_b128 v[190:193], v143 offset:20480
	ds_read_b128 v[194:197], v143 offset:21504
	ds_read_b128 v[198:201], v143 offset:22528
	ds_read_b128 v[202:205], v143 offset:23552
	global_load_lds_dwordx4 v[222:223], off
	s_mov_b32 m0, s27
	v_lshl_add_u64 v[224:225], s[18:19], 0, v[132:133]
	global_load_lds_dwordx4 v[224:225], off
	s_barrier
	s_waitcnt lgkmcnt(0)
	v_mfma_f32_16x16x32_bf16 v[94:97], v[144:147], v[160:163], 0
	v_mfma_f32_16x16x32_bf16 v[90:93], v[152:155], v[160:163], 0
	v_mfma_f32_16x16x32_bf16 v[86:89], v[144:147], v[168:171], 0
	v_mfma_f32_16x16x32_bf16 v[82:85], v[152:155], v[168:171], 0
	v_mfma_f32_16x16x32_bf16 v[78:81], v[144:147], v[190:193], 0
	v_mfma_f32_16x16x32_bf16 v[70:73], v[152:155], v[190:193], 0
	v_mfma_f32_16x16x32_bf16 v[62:65], v[144:147], v[198:201], 0
	v_mfma_f32_16x16x32_bf16 v[54:57], v[152:155], v[198:201], 0
	v_mfma_f32_16x16x32_bf16 v[94:97], v[148:151], v[164:167], v[94:97]
	v_mfma_f32_16x16x32_bf16 v[90:93], v[156:159], v[164:167], v[90:93]
	v_mfma_f32_16x16x32_bf16 v[86:89], v[148:151], v[172:175], v[86:89]
	v_mfma_f32_16x16x32_bf16 v[82:85], v[156:159], v[172:175], v[82:85]
	v_mfma_f32_16x16x32_bf16 v[78:81], v[148:151], v[194:197], v[78:81]
	v_mfma_f32_16x16x32_bf16 v[70:73], v[156:159], v[194:197], v[70:73]
	v_mfma_f32_16x16x32_bf16 v[62:65], v[148:151], v[202:205], v[62:65]
	v_mfma_f32_16x16x32_bf16 v[54:57], v[156:159], v[202:205], v[54:57]
	s_barrier
	s_add_u32 s12, s16, 0x18000
	s_addc_u32 s13, s17, 0
	s_add_i32 s0, s1, s25
	s_mov_b32 m0, s0
	v_lshl_add_u64 v[144:145], s[12:13], 0, v[4:5]
	global_load_lds_dwordx4 v[144:145], off
	s_add_i32 m0, s0, 0x2000
	v_lshl_add_u64 v[144:145], s[12:13], 0, v[130:131]
	global_load_lds_dwordx4 v[144:145], off
	s_waitcnt vmcnt(6)
	s_barrier
; #define PG8_STAGE(bufoff, gbase, voff) do { _Pragma("unroll") for (int _i = 0; _i < 2; ++_i) \
;         __builtin_amdgcn_global_load_lds((const unsigned*)((const char*)(gbase) + (voff)[_i]), (LAS unsigned*)(lds + (bufoff) + ldsw + _i * 8192), 16, 0, 0); } while (0)
; #define PG8_LDA(dst, b, h) do { _Pragma("unroll") for (int m = 0; m < 4; ++m) _Pragma("unroll") for (int k = 0; k < 2; ++k) dst[m][k] = *(const LAS bf16x8*)(lds + PG8_SA(b, h) + aoff + m * 2048 + k * 1024); } while (0)
; #define PG8_LDB(dst, b, h) do { _Pragma("unroll") for (int n = 0; n < 2; ++n) _Pragma("unroll") for (int k = 0; k < 2; ++k) dst[n][k] = *(const LAS bf16x8*)(lds + PG8_SB(b, h) + boff + n * 2048 + k * 1024); } while (0)
; #define PG8_MMA(ai, bj, At, Bt) do { __builtin_amdgcn_s_setprio(1); _Pragma("unroll") for (int m = 0; m < 4; ++m) _Pragma("unroll") for (int n = 0; n < 2; ++n) _Pragma("unroll") for (int k = 0; k < 2; ++k) \
;         acc[ai][bj][m][n] = __builtin_amdgcn_mfma_f32_16x16x32_bf16(Bt[n][k], At[m][k], acc[ai][bj][m][n], 0, 0, 0); __builtin_amdgcn_s_setprio(0); } while (0)
; #define PG8_WAIT_V(n) asm volatile("s_waitcnt vmcnt(" #n ")" ::: "memory")
; #define PG8_WAIT_L(n) asm volatile("s_waitcnt lgkmcnt(" #n ")" ::: "memory")
; #define PG8_BAR __builtin_amdgcn_s_barrier()
; #define PG8_SCHED __builtin_amdgcn_sched_barrier(0)
; template <class Epi>
; __device__ __forceinline__ void gemm_phase(LAS unsigned char* lds, const Gemm g, const StaticOrder& S, const Epi& E) {
;     ...
;             PG8_WAIT_V(6); PG8_BAR; PG8_MMA(1, 1, At, B1); PG8_BAR;
;             PG8_LDB(B0, 1, 0); PG8_SCHED; PG8_LDA(At, 1, 0); PG8_STAGE(PG8_SA(0, 1), a2 + hstep, voffA);
;             PG8_WAIT_L(8); PG8_BAR; PG8_WAIT_L(0); PG8_MMA(0, 0, At, B0); PG8_BAR; PG8_SCHED;
;             PG8_LDB(B1, 1, 1); PG8_STAGE(PG8_SB(1, 0), b3, voffB);
;             PG8_BAR; PG8_WAIT_L(0); PG8_MMA(0, 1, At, B1); PG8_BAR;
	v_mfma_f32_16x16x32_bf16 v[30:33], v[206:209], v[160:163], 0
	v_mfma_f32_16x16x32_bf16 v[26:29], v[214:217], v[160:163], 0
	v_mfma_f32_16x16x32_bf16 v[22:25], v[206:209], v[168:171], 0
	v_mfma_f32_16x16x32_bf16 v[18:21], v[214:217], v[168:171], 0
	v_mfma_f32_16x16x32_bf16 v[14:17], v[206:209], v[190:193], 0
	v_mfma_f32_16x16x32_bf16 v[10:13], v[214:217], v[190:193], 0
	v_mfma_f32_16x16x32_bf16 v[6:9], v[206:209], v[198:201], 0
	v_mfma_f32_16x16x32_bf16 v[0:3], v[214:217], v[198:201], 0
	v_mfma_f32_16x16x32_bf16 v[30:33], v[210:213], v[164:167], v[30:33]
	v_mfma_f32_16x16x32_bf16 v[26:29], v[218:221], v[164:167], v[26:29]
	v_mfma_f32_16x16x32_bf16 v[22:25], v[210:213], v[172:175], v[22:25]
	v_mfma_f32_16x16x32_bf16 v[18:21], v[218:221], v[172:175], v[18:21]
	v_mfma_f32_16x16x32_bf16 v[14:17], v[210:213], v[194:197], v[14:17]
	v_mfma_f32_16x16x32_bf16 v[10:13], v[218:221], v[194:197], v[10:13]
	v_mfma_f32_16x16x32_bf16 v[6:9], v[210:213], v[202:205], v[6:9]
	v_mfma_f32_16x16x32_bf16 v[0:3], v[218:221], v[202:205], v[0:3]
	s_add_i32 s0, 0, 0x18000
	v_add_u32_e32 v156, s0, v141
	s_barrier
	ds_read_b128 v[144:147], v156
	ds_read_b128 v[148:151], v156 offset:1024
	ds_read_b128 v[152:155], v156 offset:2048
	ds_read_b128 v[156:159], v156 offset:3072
	s_add_u32 s12, s18, 0x18000
	s_addc_u32 s13, s19, 0
	s_mov_b32 m0, s28
	v_lshl_add_u64 v[206:207], s[12:13], 0, v[134:135]
	ds_read_b128 v[160:163], v143 offset:32768
	ds_read_b128 v[164:167], v143 offset:33792
	ds_read_b128 v[168:171], v143 offset:34816
	ds_read_b128 v[172:175], v143 offset:35840
	ds_read_b128 v[190:193], v143 offset:36864
	ds_read_b128 v[194:197], v143 offset:37888
	ds_read_b128 v[198:201], v143 offset:38912
	ds_read_b128 v[202:205], v143 offset:39936
	global_load_lds_dwordx4 v[206:207], off
	s_mov_b32 m0, s29
	v_lshl_add_u64 v[206:207], s[12:13], 0, v[132:133]
	global_load_lds_dwordx4 v[206:207], off
	s_waitcnt lgkmcnt(8)
	s_barrier
	s_waitcnt lgkmcnt(0)
	v_mfma_f32_16x16x32_bf16 v[126:129], v[144:147], v[160:163], v[126:129]
	v_mfma_f32_16x16x32_bf16 v[122:125], v[152:155], v[160:163], v[122:125]
	v_mfma_f32_16x16x32_bf16 v[118:121], v[144:147], v[168:171], v[118:121]
	v_mfma_f32_16x16x32_bf16 v[114:117], v[152:155], v[168:171], v[114:117]
	v_mfma_f32_16x16x32_bf16 v[110:113], v[144:147], v[190:193], v[110:113]
	v_mfma_f32_16x16x32_bf16 v[106:109], v[152:155], v[190:193], v[106:109]
	v_mfma_f32_16x16x32_bf16 v[102:105], v[144:147], v[198:201], v[102:105]
	v_mfma_f32_16x16x32_bf16 v[98:101], v[152:155], v[198:201], v[98:101]
	v_mfma_f32_16x16x32_bf16 v[126:129], v[148:151], v[164:167], v[126:129]
	v_mfma_f32_16x16x32_bf16 v[122:125], v[156:159], v[164:167], v[122:125]
	v_mfma_f32_16x16x32_bf16 v[118:121], v[148:151], v[172:175], v[118:121]
	v_mfma_f32_16x16x32_bf16 v[114:117], v[156:159], v[172:175], v[114:117]
	v_mfma_f32_16x16x32_bf16 v[110:113], v[148:151], v[194:197], v[110:113]
	v_mfma_f32_16x16x32_bf16 v[106:109], v[156:159], v[194:197], v[106:109]
	v_mfma_f32_16x16x32_bf16 v[102:105], v[148:151], v[202:205], v[102:105]
	v_mfma_f32_16x16x32_bf16 v[98:101], v[156:159], v[202:205], v[98:101]
	s_barrier
	s_add_i32 s1, 0, 0x1c000
	s_add_i32 s0, s0, s25
	v_add_u32_e32 v218, s1, v141
	v_lshl_add_u64 v[176:177], v[176:177], 0, s[86:87]
	s_mov_b32 m0, s0
	ds_read_b128 v[206:209], v218
	ds_read_b128 v[210:213], v218 offset:1024
	ds_read_b128 v[214:217], v218 offset:2048
	ds_read_b128 v[218:221], v218 offset:3072
	global_load_lds_dwordx4 v[176:177], off
	s_add_i32 m0, s0, 0x2000
	v_lshl_add_u64 v[176:177], v[186:187], 0, s[86:87]
	global_load_lds_dwordx4 v[176:177], off
	s_barrier
; #define PG8_STAGE(bufoff, gbase, voff) do { _Pragma("unroll") for (int _i = 0; _i < 2; ++_i) \
;         __builtin_amdgcn_global_load_lds((const unsigned*)((const char*)(gbase) + (voff)[_i]), (LAS unsigned*)(lds + (bufoff) + ldsw + _i * 8192), 16, 0, 0); } while (0)
; #define PG8_LDA(dst, b, h) do { _Pragma("unroll") for (int m = 0; m < 4; ++m) _Pragma("unroll") for (int k = 0; k < 2; ++k) dst[m][k] = *(const LAS bf16x8*)(lds + PG8_SA(b, h) + aoff + m * 2048 + k * 1024); } while (0)
; #define PG8_MMA(ai, bj, At, Bt) do { __builtin_amdgcn_s_setprio(1); _Pragma("unroll") for (int m = 0; m < 4; ++m) _Pragma("unroll") for (int n = 0; n < 2; ++n) _Pragma("unroll") for (int k = 0; k < 2; ++k) \
;         acc[ai][bj][m][n] = __builtin_amdgcn_mfma_f32_16x16x32_bf16(Bt[n][k], At[m][k], acc[ai][bj][m][n], 0, 0, 0); __builtin_amdgcn_s_setprio(0); } while (0)
; #define PG8_WAIT_V(n) asm volatile("s_waitcnt vmcnt(" #n ")" ::: "memory")
; #define PG8_WAIT_L(n) asm volatile("s_waitcnt lgkmcnt(" #n ")" ::: "memory")
; #define PG8_BAR __builtin_amdgcn_s_barrier()
; #define PG8_SCHED __builtin_amdgcn_sched_barrier(0)
; template <class Epi>
; __device__ __forceinline__ void gemm_phase(LAS unsigned char* lds, const Gemm g, const StaticOrder& S, const Epi& E) {
;     ...
;             PG8_BAR; PG8_WAIT_L(0); PG8_MMA(0, 1, At, B1); PG8_BAR;
;             PG8_LDA(At, 1, 1); PG8_STAGE(PG8_SA(1, 0), a3, voffA);
;             PG8_BAR; PG8_WAIT_L(0); PG8_MMA(1, 0, At, B0); PG8_BAR; PG8_SCHED;
;             PG8_STAGE(PG8_SB(1, 1), b3 + hstep, voffB);
;             PG8_WAIT_V(6); PG8_BAR; PG8_MMA(1, 1, At, B1); PG8_BAR;
;         }
	s_waitcnt lgkmcnt(0)
	v_mfma_f32_16x16x32_bf16 v[74:77], v[206:209], v[160:163], v[74:77]
	v_mfma_f32_16x16x32_bf16 v[66:69], v[214:217], v[160:163], v[66:69]
	v_mfma_f32_16x16x32_bf16 v[58:61], v[206:209], v[168:171], v[58:61]
	v_mfma_f32_16x16x32_bf16 v[50:53], v[214:217], v[168:171], v[50:53]
	v_mfma_f32_16x16x32_bf16 v[46:49], v[206:209], v[190:193], v[46:49]
	v_mfma_f32_16x16x32_bf16 v[42:45], v[214:217], v[190:193], v[42:45]
	v_mfma_f32_16x16x32_bf16 v[38:41], v[206:209], v[198:201], v[38:41]
	v_mfma_f32_16x16x32_bf16 v[34:37], v[214:217], v[198:201], v[34:37]
	v_mfma_f32_16x16x32_bf16 v[74:77], v[210:213], v[164:167], v[74:77]
	v_mfma_f32_16x16x32_bf16 v[66:69], v[218:221], v[164:167], v[66:69]
	v_mfma_f32_16x16x32_bf16 v[58:61], v[210:213], v[172:175], v[58:61]
	v_mfma_f32_16x16x32_bf16 v[50:53], v[218:221], v[172:175], v[50:53]
	v_mfma_f32_16x16x32_bf16 v[46:49], v[210:213], v[194:197], v[46:49]
	v_mfma_f32_16x16x32_bf16 v[42:45], v[218:221], v[194:197], v[42:45]
	v_mfma_f32_16x16x32_bf16 v[38:41], v[210:213], v[202:205], v[38:41]
	v_mfma_f32_16x16x32_bf16 v[34:37], v[218:221], v[202:205], v[34:37]
	s_mov_b32 m0, s30
	v_lshl_add_u64 v[176:177], v[222:223], 0, s[86:87]
	s_barrier
	ds_read_b128 v[160:163], v143 offset:49152
	ds_read_b128 v[164:167], v143 offset:50176
	ds_read_b128 v[168:171], v143 offset:51200
	ds_read_b128 v[172:175], v143 offset:52224
	ds_read_b128 v[190:193], v143 offset:53248
	ds_read_b128 v[194:197], v143 offset:54272
	ds_read_b128 v[198:201], v143 offset:55296
	ds_read_b128 v[202:205], v143 offset:56320
	global_load_lds_dwordx4 v[176:177], off
	s_mov_b32 m0, s31
	v_lshl_add_u64 v[176:177], v[224:225], 0, s[86:87]
	global_load_lds_dwordx4 v[176:177], off
	s_barrier
	s_waitcnt lgkmcnt(0)
	v_mfma_f32_16x16x32_bf16 v[94:97], v[144:147], v[160:163], v[94:97]
	v_mfma_f32_16x16x32_bf16 v[90:93], v[152:155], v[160:163], v[90:93]
	v_mfma_f32_16x16x32_bf16 v[86:89], v[144:147], v[168:171], v[86:89]
	v_mfma_f32_16x16x32_bf16 v[82:85], v[152:155], v[168:171], v[82:85]
	v_mfma_f32_16x16x32_bf16 v[78:81], v[144:147], v[190:193], v[78:81]
	v_mfma_f32_16x16x32_bf16 v[70:73], v[152:155], v[190:193], v[70:73]
	v_mfma_f32_16x16x32_bf16 v[62:65], v[144:147], v[198:201], v[62:65]
	v_mfma_f32_16x16x32_bf16 v[54:57], v[152:155], v[198:201], v[54:57]
	v_mfma_f32_16x16x32_bf16 v[94:97], v[148:151], v[164:167], v[94:97]
	v_mfma_f32_16x16x32_bf16 v[90:93], v[156:159], v[164:167], v[90:93]
	v_mfma_f32_16x16x32_bf16 v[86:89], v[148:151], v[172:175], v[86:89]
	v_mfma_f32_16x16x32_bf16 v[82:85], v[156:159], v[172:175], v[82:85]
	v_mfma_f32_16x16x32_bf16 v[78:81], v[148:151], v[194:197], v[78:81]
	v_mfma_f32_16x16x32_bf16 v[70:73], v[156:159], v[194:197], v[70:73]
	v_mfma_f32_16x16x32_bf16 v[62:65], v[148:151], v[202:205], v[62:65]
	v_mfma_f32_16x16x32_bf16 v[54:57], v[156:159], v[202:205], v[54:57]
	s_barrier
	s_add_u32 s12, s16, 0x18080
	s_addc_u32 s13, s17, 0
	s_add_i32 s0, s1, s25
	s_mov_b32 m0, s0
	v_lshl_add_u64 v[144:145], s[12:13], 0, v[4:5]
	global_load_lds_dwordx4 v[144:145], off
	s_add_i32 m0, s0, 0x2000
	v_lshl_add_u64 v[144:145], s[12:13], 0, v[130:131]
	global_load_lds_dwordx4 v[144:145], off
	s_waitcnt vmcnt(6)
	s_barrier
	v_mfma_f32_16x16x32_bf16 v[30:33], v[206:209], v[160:163], v[30:33]
	v_mfma_f32_16x16x32_bf16 v[26:29], v[214:217], v[160:163], v[26:29]
	v_mfma_f32_16x16x32_bf16 v[22:25], v[206:209], v[168:171], v[22:25]
	v_mfma_f32_16x16x32_bf16 v[18:21], v[214:217], v[168:171], v[18:21]
	v_mfma_f32_16x16x32_bf16 v[14:17], v[206:209], v[190:193], v[14:17]
	v_mfma_f32_16x16x32_bf16 v[10:13], v[214:217], v[190:193], v[10:13]
	v_mfma_f32_16x16x32_bf16 v[6:9], v[206:209], v[198:201], v[6:9]
	v_mfma_f32_16x16x32_bf16 v[0:3], v[214:217], v[198:201], v[0:3]
	v_mfma_f32_16x16x32_bf16 v[30:33], v[210:213], v[164:167], v[30:33]
	v_mfma_f32_16x16x32_bf16 v[26:29], v[218:221], v[164:167], v[26:29]
	v_mfma_f32_16x16x32_bf16 v[22:25], v[210:213], v[172:175], v[22:25]
	v_mfma_f32_16x16x32_bf16 v[18:21], v[218:221], v[172:175], v[18:21]
	v_mfma_f32_16x16x32_bf16 v[14:17], v[210:213], v[194:197], v[14:17]
	v_mfma_f32_16x16x32_bf16 v[10:13], v[218:221], v[194:197], v[10:13]
	v_mfma_f32_16x16x32_bf16 v[6:9], v[210:213], v[202:205], v[6:9]
	v_mfma_f32_16x16x32_bf16 v[0:3], v[218:221], v[202:205], v[0:3]
	s_add_i32 s41, s41, 2
	s_add_u32 s39, s39, 0x100
	s_addc_u32 s40, s40, 0
	s_cmp_gt_u32 s41, 3
	s_mov_b64 s[12:13], s[14:15]
	s_barrier
	s_cbranch_scc1 .Lpeel_exit_4
	.p2align 6

; __device__ __forceinline__ void phase_rwkv(KP P, int l_, unsigned char* shm) {
;     ...
;                 for (int tl = 0; tl < T; tl += 2) {
;                     RW_LD(B, tl + 1);
;                     RW_STEP(A, tl);
;                     RW_LD(A, tl + 2);
;                     RW_STEP(B, tl + 1);
;                 }
.LBB0_2516:
	s_add_i32 s52, s52, 4
	v_add_u32_e32 v253, 0x400, v253
	v_add_u32_e32 v235, 0x400, v235
	s_cmp_gt_u32 s52, 29
	v_add_u32_e32 v252, 0x400, v252
	s_cbranch_scc1 .LBB0_2489
	.p2align 6

; __device__ __forceinline__ void phase_attn(KP P, int l_, unsigned char* shm) {
;     ...
;         for (int t = 0; t < nt; ++t) {
;             if (t + 1 < nt) ATT_GLOAD(t + 1);
;     ...
;             if (t + 1 < nt) ATT_LSTORE((t + 1) & 1);
;             __syncthreads();
.LBB0_2650:
	s_mov_b64 s[56:57], 0x100
	s_add_i32 s52, s52, 2
	v_lshl_add_u64 v[174:175], v[174:175], 0, s[56:57]
	s_mov_b64 s[56:57], 0x60000
	s_cmp_eq_u32 s65, s52
	v_lshl_add_u64 v[176:177], v[176:177], 0, s[56:57]
	s_waitcnt vmcnt(0) lgkmcnt(0)
	s_barrier
	s_cbranch_scc1 .LBB0_2663
	.p2align 6

; #define PG8_STAGE(bufoff, gbase, voff) do { _Pragma("unroll") for (int _i = 0; _i < 2; ++_i) \
;         __builtin_amdgcn_global_load_lds((const unsigned*)((const char*)(gbase) + (voff)[_i]), (LAS unsigned*)(lds + (bufoff) + ldsw + _i * 8192), 16, 0, 0); } while (0)
; #define PG8_LDA(dst, b, h) do { _Pragma("unroll") for (int m = 0; m < 4; ++m) _Pragma("unroll") for (int k = 0; k < 2; ++k) dst[m][k] = *(const LAS bf16x8*)(lds + PG8_SA(b, h) + aoff + m * 2048 + k * 1024); } while (0)
; #define PG8_LDB(dst, b, h) do { _Pragma("unroll") for (int n = 0; n < 2; ++n) _Pragma("unroll") for (int k = 0; k < 2; ++k) dst[n][k] = *(const LAS bf16x8*)(lds + PG8_SB(b, h) + boff + n * 2048 + k * 1024); } while (0)
; #define PG8_MMA(ai, bj, At, Bt) do { __builtin_amdgcn_s_setprio(1); _Pragma("unroll") for (int m = 0; m < 4; ++m) _Pragma("unroll") for (int n = 0; n < 2; ++n) _Pragma("unroll") for (int k = 0; k < 2; ++k) \
;         acc[ai][bj][m][n] = __builtin_amdgcn_mfma_f32_16x16x32_bf16(Bt[n][k], At[m][k], acc[ai][bj][m][n], 0, 0, 0); __builtin_amdgcn_s_setprio(0); } while (0)
; #define PG8_WAIT_V(n) asm volatile("s_waitcnt vmcnt(" #n ")" ::: "memory")
; #define PG8_WAIT_L(n) asm volatile("s_waitcnt lgkmcnt(" #n ")" ::: "memory")
; #define PG8_BAR __builtin_amdgcn_s_barrier()
; template <class Epi>
; __device__ __forceinline__ void gemm_phase(LAS unsigned char* lds, const Gemm g, const StaticOrder& S, const Epi& E) {
;     ...
;             const bool last = (t == nt - 2);
;             const char* a1 = cA + (size_t)(t + 1) * kstep;
;             const char* a2 = last ? nA : cA + (size_t)(t + 2) * kstep; const char* b2 = last ? nB : cB + (size_t)(t + 2) * kstep;
;             const char* a3 = a2 + kstep; const char* b3 = b2 + kstep;
;             PG8_LDB(B0, 0, 0); PG8_SCHED; PG8_LDA(At, 0, 0); PG8_STAGE(PG8_SA(1, 1), a1 + hstep, voffA);
;             PG8_WAIT_L(8); PG8_BAR; PG8_WAIT_L(0); PG8_MMA(0, 0, At, B0); PG8_BAR; PG8_SCHED;
;             PG8_LDB(B1, 0, 1); PG8_STAGE(PG8_SB(0, 0), b2, voffB);
;             PG8_BAR; PG8_WAIT_L(0); PG8_MMA(0, 1, At, B1); PG8_BAR;
;             PG8_LDA(At, 0, 1); PG8_STAGE(PG8_SA(0, 0), a2, voffA);
;             PG8_BAR; PG8_WAIT_L(0); PG8_MMA(1, 0, At, B0); PG8_BAR; PG8_SCHED;
;             PG8_STAGE(PG8_SB(0, 1), b2 + hstep, voffB);
;             PG8_WAIT_V(6); PG8_BAR; PG8_MMA(1, 1, At, B1); PG8_BAR;
.Lsp_skip_3:
	s_add_u32 s0, s16, 0xfffe0080
	s_addc_u32 s1, s17, -1
	s_add_i32 s48, 0, 0x10000
	v_add_u32_e32 v156, s48, v141
	ds_read_b128 v[144:147], v156
	ds_read_b128 v[148:151], v156 offset:1024
	ds_read_b128 v[152:155], v156 offset:2048
	ds_read_b128 v[156:159], v156 offset:3072
	s_cmp_eq_u32 s43, 4
	s_cselect_b32 s21, s11, s1
	s_cselect_b32 s20, s39, s0
	s_cselect_b32 s19, s9, s42
	s_cselect_b32 s18, s40, s41
	v_lshl_add_u64 v[176:177], s[16:17], 0, v[136:137]
	s_add_i32 m0, s28, 0xc000
	ds_read_b128 v[160:163], v143
	ds_read_b128 v[164:167], v143 offset:1024
	ds_read_b128 v[168:171], v143 offset:2048
	ds_read_b128 v[172:175], v143 offset:3072
	ds_read_b128 v[190:193], v143 offset:4096
	ds_read_b128 v[194:197], v143 offset:5120
	ds_read_b128 v[198:201], v143 offset:6144
	ds_read_b128 v[202:205], v143 offset:7168
	global_load_lds_dwordx4 v[176:177], off
	s_add_i32 m0, s28, 0xe000
	v_lshl_add_u64 v[176:177], s[16:17], 0, v[138:139]
	global_load_lds_dwordx4 v[176:177], off
	s_waitcnt lgkmcnt(8)
	s_barrier
	s_waitcnt lgkmcnt(0)
	v_mfma_f32_16x16x32_bf16 v[126:129], v[144:147], v[160:163], 0
	v_mfma_f32_16x16x32_bf16 v[122:125], v[152:155], v[160:163], 0
	v_mfma_f32_16x16x32_bf16 v[118:121], v[144:147], v[168:171], 0
	v_mfma_f32_16x16x32_bf16 v[114:117], v[152:155], v[168:171], 0
	v_mfma_f32_16x16x32_bf16 v[110:113], v[144:147], v[190:193], 0
	v_mfma_f32_16x16x32_bf16 v[106:109], v[152:155], v[190:193], 0
	v_mfma_f32_16x16x32_bf16 v[102:105], v[144:147], v[198:201], 0
	v_mfma_f32_16x16x32_bf16 v[98:101], v[152:155], v[198:201], 0
	v_mfma_f32_16x16x32_bf16 v[126:129], v[148:151], v[164:167], v[126:129]
	v_mfma_f32_16x16x32_bf16 v[122:125], v[156:159], v[164:167], v[122:125]
	v_mfma_f32_16x16x32_bf16 v[118:121], v[148:151], v[172:175], v[118:121]
	v_mfma_f32_16x16x32_bf16 v[114:117], v[156:159], v[172:175], v[114:117]
	v_mfma_f32_16x16x32_bf16 v[110:113], v[148:151], v[194:197], v[110:113]
	v_mfma_f32_16x16x32_bf16 v[106:109], v[156:159], v[194:197], v[106:109]
	v_mfma_f32_16x16x32_bf16 v[102:105], v[148:151], v[202:205], v[102:105]
	v_mfma_f32_16x16x32_bf16 v[98:101], v[156:159], v[202:205], v[98:101]
	s_barrier
	s_add_i32 s49, 0, 0x14000
	v_add_u32_e32 v176, s49, v141
	s_add_i32 s0, s48, s27
	ds_read_b128 v[206:209], v176
	ds_read_b128 v[210:213], v176 offset:1024
	ds_read_b128 v[214:217], v176 offset:2048
	ds_read_b128 v[218:221], v176 offset:3072
	v_lshl_add_u64 v[176:177], s[18:19], 0, v[4:5]
	s_mov_b32 m0, s0
	v_lshl_add_u64 v[186:187], s[18:19], 0, v[130:131]
	global_load_lds_dwordx4 v[176:177], off
	s_add_i32 m0, s0, 0x2000
	s_nop 0
	global_load_lds_dwordx4 v[186:187], off
	s_barrier
	s_waitcnt lgkmcnt(0)
	v_mfma_f32_16x16x32_bf16 v[70:73], v[206:209], v[160:163], 0
	v_mfma_f32_16x16x32_bf16 v[66:69], v[214:217], v[160:163], 0
	v_mfma_f32_16x16x32_bf16 v[54:57], v[206:209], v[168:171], 0
	v_mfma_f32_16x16x32_bf16 v[50:53], v[214:217], v[168:171], 0
	v_mfma_f32_16x16x32_bf16 v[46:49], v[206:209], v[190:193], 0
	v_mfma_f32_16x16x32_bf16 v[42:45], v[214:217], v[190:193], 0
	v_mfma_f32_16x16x32_bf16 v[38:41], v[206:209], v[198:201], 0
	v_mfma_f32_16x16x32_bf16 v[34:37], v[214:217], v[198:201], 0
	v_mfma_f32_16x16x32_bf16 v[70:73], v[210:213], v[164:167], v[70:73]
	v_mfma_f32_16x16x32_bf16 v[66:69], v[218:221], v[164:167], v[66:69]
	v_mfma_f32_16x16x32_bf16 v[54:57], v[210:213], v[172:175], v[54:57]
	v_mfma_f32_16x16x32_bf16 v[50:53], v[218:221], v[172:175], v[50:53]
	v_mfma_f32_16x16x32_bf16 v[46:49], v[210:213], v[194:197], v[46:49]
	v_mfma_f32_16x16x32_bf16 v[42:45], v[218:221], v[194:197], v[42:45]
	v_mfma_f32_16x16x32_bf16 v[38:41], v[210:213], v[202:205], v[38:41]
	v_mfma_f32_16x16x32_bf16 v[34:37], v[218:221], v[202:205], v[34:37]
	s_mov_b32 m0, s28
	v_lshl_add_u64 v[222:223], s[20:21], 0, v[134:135]
	s_barrier
	ds_read_b128 v[160:163], v143 offset:16384
	ds_read_b128 v[164:167], v143 offset:17408
	ds_read_b128 v[168:171], v143 offset:18432
	ds_read_b128 v[172:175], v143 offset:19456
	ds_read_b128 v[190:193], v143 offset:20480
	ds_read_b128 v[194:197], v143 offset:21504
	ds_read_b128 v[198:201], v143 offset:22528
	ds_read_b128 v[202:205], v143 offset:23552
	global_load_lds_dwordx4 v[222:223], off
	s_mov_b32 m0, s29
	v_lshl_add_u64 v[224:225], s[20:21], 0, v[132:133]
	global_load_lds_dwordx4 v[224:225], off
	s_barrier
	s_waitcnt lgkmcnt(0)
	v_mfma_f32_16x16x32_bf16 v[94:97], v[144:147], v[160:163], 0
	v_mfma_f32_16x16x32_bf16 v[90:93], v[152:155], v[160:163], 0
	v_mfma_f32_16x16x32_bf16 v[86:89], v[144:147], v[168:171], 0
	v_mfma_f32_16x16x32_bf16 v[82:85], v[152:155], v[168:171], 0
	v_mfma_f32_16x16x32_bf16 v[78:81], v[144:147], v[190:193], 0
	v_mfma_f32_16x16x32_bf16 v[74:77], v[152:155], v[190:193], 0
	v_mfma_f32_16x16x32_bf16 v[62:65], v[144:147], v[198:201], 0
	v_mfma_f32_16x16x32_bf16 v[58:61], v[152:155], v[198:201], 0
	v_mfma_f32_16x16x32_bf16 v[94:97], v[148:151], v[164:167], v[94:97]
	v_mfma_f32_16x16x32_bf16 v[90:93], v[156:159], v[164:167], v[90:93]
	v_mfma_f32_16x16x32_bf16 v[86:89], v[148:151], v[172:175], v[86:89]
	v_mfma_f32_16x16x32_bf16 v[82:85], v[156:159], v[172:175], v[82:85]
	v_mfma_f32_16x16x32_bf16 v[78:81], v[148:151], v[194:197], v[78:81]
	v_mfma_f32_16x16x32_bf16 v[74:77], v[156:159], v[194:197], v[74:77]
	v_mfma_f32_16x16x32_bf16 v[62:65], v[148:151], v[202:205], v[62:65]
	v_mfma_f32_16x16x32_bf16 v[58:61], v[156:159], v[202:205], v[58:61]
	s_barrier
	s_add_u32 s0, s18, 0x20000
	s_addc_u32 s1, s19, 0
	s_add_i32 s48, s49, s27
	s_mov_b32 m0, s48
	v_lshl_add_u64 v[144:145], s[0:1], 0, v[4:5]
	global_load_lds_dwordx4 v[144:145], off
	s_add_i32 m0, s48, 0x2000
	v_lshl_add_u64 v[144:145], s[0:1], 0, v[130:131]
	global_load_lds_dwordx4 v[144:145], off
	s_waitcnt vmcnt(6)
	s_barrier
; #define PG8_STAGE(bufoff, gbase, voff) do { _Pragma("unroll") for (int _i = 0; _i < 2; ++_i) \
;         __builtin_amdgcn_global_load_lds((const unsigned*)((const char*)(gbase) + (voff)[_i]), (LAS unsigned*)(lds + (bufoff) + ldsw + _i * 8192), 16, 0, 0); } while (0)
; #define PG8_LDA(dst, b, h) do { _Pragma("unroll") for (int m = 0; m < 4; ++m) _Pragma("unroll") for (int k = 0; k < 2; ++k) dst[m][k] = *(const LAS bf16x8*)(lds + PG8_SA(b, h) + aoff + m * 2048 + k * 1024); } while (0)
; #define PG8_LDB(dst, b, h) do { _Pragma("unroll") for (int n = 0; n < 2; ++n) _Pragma("unroll") for (int k = 0; k < 2; ++k) dst[n][k] = *(const LAS bf16x8*)(lds + PG8_SB(b, h) + boff + n * 2048 + k * 1024); } while (0)
; #define PG8_MMA(ai, bj, At, Bt) do { __builtin_amdgcn_s_setprio(1); _Pragma("unroll") for (int m = 0; m < 4; ++m) _Pragma("unroll") for (int n = 0; n < 2; ++n) _Pragma("unroll") for (int k = 0; k < 2; ++k) \
;         acc[ai][bj][m][n] = __builtin_amdgcn_mfma_f32_16x16x32_bf16(Bt[n][k], At[m][k], acc[ai][bj][m][n], 0, 0, 0); __builtin_amdgcn_s_setprio(0); } while (0)
; #define PG8_WAIT_V(n) asm volatile("s_waitcnt vmcnt(" #n ")" ::: "memory")
; #define PG8_WAIT_L(n) asm volatile("s_waitcnt lgkmcnt(" #n ")" ::: "memory")
; #define PG8_BAR __builtin_amdgcn_s_barrier()
; #define PG8_SCHED __builtin_amdgcn_sched_barrier(0)
; template <class Epi>
; __device__ __forceinline__ void gemm_phase(LAS unsigned char* lds, const Gemm g, const StaticOrder& S, const Epi& E) {
;     ...
;             PG8_WAIT_V(6); PG8_BAR; PG8_MMA(1, 1, At, B1); PG8_BAR;
;             PG8_LDB(B0, 1, 0); PG8_SCHED; PG8_LDA(At, 1, 0); PG8_STAGE(PG8_SA(0, 1), a2 + hstep, voffA);
;             PG8_WAIT_L(8); PG8_BAR; PG8_WAIT_L(0); PG8_MMA(0, 0, At, B0); PG8_BAR; PG8_SCHED;
;             PG8_LDB(B1, 1, 1); PG8_STAGE(PG8_SB(1, 0), b3, voffB);
;             PG8_BAR; PG8_WAIT_L(0); PG8_MMA(0, 1, At, B1); PG8_BAR;
	v_mfma_f32_16x16x32_bf16 v[30:33], v[206:209], v[160:163], 0
	v_mfma_f32_16x16x32_bf16 v[26:29], v[214:217], v[160:163], 0
	v_mfma_f32_16x16x32_bf16 v[22:25], v[206:209], v[168:171], 0
	v_mfma_f32_16x16x32_bf16 v[18:21], v[214:217], v[168:171], 0
	v_mfma_f32_16x16x32_bf16 v[14:17], v[206:209], v[190:193], 0
	v_mfma_f32_16x16x32_bf16 v[10:13], v[214:217], v[190:193], 0
	v_mfma_f32_16x16x32_bf16 v[6:9], v[206:209], v[198:201], 0
	v_mfma_f32_16x16x32_bf16 v[0:3], v[214:217], v[198:201], 0
	v_mfma_f32_16x16x32_bf16 v[30:33], v[210:213], v[164:167], v[30:33]
	v_mfma_f32_16x16x32_bf16 v[26:29], v[218:221], v[164:167], v[26:29]
	v_mfma_f32_16x16x32_bf16 v[22:25], v[210:213], v[172:175], v[22:25]
	v_mfma_f32_16x16x32_bf16 v[18:21], v[218:221], v[172:175], v[18:21]
	v_mfma_f32_16x16x32_bf16 v[14:17], v[210:213], v[194:197], v[14:17]
	v_mfma_f32_16x16x32_bf16 v[10:13], v[218:221], v[194:197], v[10:13]
	v_mfma_f32_16x16x32_bf16 v[6:9], v[210:213], v[202:205], v[6:9]
	v_mfma_f32_16x16x32_bf16 v[0:3], v[218:221], v[202:205], v[0:3]
	s_add_i32 s48, 0, 0x18000
	v_add_u32_e32 v156, s48, v141
	s_barrier
	ds_read_b128 v[144:147], v156
	ds_read_b128 v[148:151], v156 offset:1024
	ds_read_b128 v[152:155], v156 offset:2048
	ds_read_b128 v[156:159], v156 offset:3072
	s_add_u32 s0, s20, 0x20000
	s_addc_u32 s1, s21, 0
	s_mov_b32 m0, s30
	v_lshl_add_u64 v[206:207], s[0:1], 0, v[134:135]
	ds_read_b128 v[160:163], v143 offset:32768
	ds_read_b128 v[164:167], v143 offset:33792
	ds_read_b128 v[168:171], v143 offset:34816
	ds_read_b128 v[172:175], v143 offset:35840
	ds_read_b128 v[190:193], v143 offset:36864
	ds_read_b128 v[194:197], v143 offset:37888
	ds_read_b128 v[198:201], v143 offset:38912
	ds_read_b128 v[202:205], v143 offset:39936
	global_load_lds_dwordx4 v[206:207], off
	s_mov_b32 m0, s31
	v_lshl_add_u64 v[206:207], s[0:1], 0, v[132:133]
	global_load_lds_dwordx4 v[206:207], off
	s_waitcnt lgkmcnt(8)
	s_barrier
	s_waitcnt lgkmcnt(0)
	v_mfma_f32_16x16x32_bf16 v[126:129], v[144:147], v[160:163], v[126:129]
	v_mfma_f32_16x16x32_bf16 v[122:125], v[152:155], v[160:163], v[122:125]
	v_mfma_f32_16x16x32_bf16 v[118:121], v[144:147], v[168:171], v[118:121]
	v_mfma_f32_16x16x32_bf16 v[114:117], v[152:155], v[168:171], v[114:117]
	v_mfma_f32_16x16x32_bf16 v[110:113], v[144:147], v[190:193], v[110:113]
	v_mfma_f32_16x16x32_bf16 v[106:109], v[152:155], v[190:193], v[106:109]
	v_mfma_f32_16x16x32_bf16 v[102:105], v[144:147], v[198:201], v[102:105]
	v_mfma_f32_16x16x32_bf16 v[98:101], v[152:155], v[198:201], v[98:101]
	v_mfma_f32_16x16x32_bf16 v[126:129], v[148:151], v[164:167], v[126:129]
	v_mfma_f32_16x16x32_bf16 v[122:125], v[156:159], v[164:167], v[122:125]
	v_mfma_f32_16x16x32_bf16 v[118:121], v[148:151], v[172:175], v[118:121]
	v_mfma_f32_16x16x32_bf16 v[114:117], v[156:159], v[172:175], v[114:117]
	v_mfma_f32_16x16x32_bf16 v[110:113], v[148:151], v[194:197], v[110:113]
	v_mfma_f32_16x16x32_bf16 v[106:109], v[156:159], v[194:197], v[106:109]
	v_mfma_f32_16x16x32_bf16 v[102:105], v[148:151], v[202:205], v[102:105]
	v_mfma_f32_16x16x32_bf16 v[98:101], v[156:159], v[202:205], v[98:101]
	s_barrier
	s_add_i32 s20, 0, 0x1c000
	s_add_i32 s0, s48, s27
	v_add_u32_e32 v218, s20, v141
	v_lshl_add_u64 v[176:177], v[176:177], 0, s[86:87]
	s_mov_b32 m0, s0
	ds_read_b128 v[206:209], v218
	ds_read_b128 v[210:213], v218 offset:1024
	ds_read_b128 v[214:217], v218 offset:2048
	ds_read_b128 v[218:221], v218 offset:3072
	global_load_lds_dwordx4 v[176:177], off
	s_add_i32 m0, s0, 0x2000
	v_lshl_add_u64 v[176:177], v[186:187], 0, s[86:87]
	global_load_lds_dwordx4 v[176:177], off
	s_barrier
; #define PG8_STAGE(bufoff, gbase, voff) do { _Pragma("unroll") for (int _i = 0; _i < 2; ++_i) \
;         __builtin_amdgcn_global_load_lds((const unsigned*)((const char*)(gbase) + (voff)[_i]), (LAS unsigned*)(lds + (bufoff) + ldsw + _i * 8192), 16, 0, 0); } while (0)
; #define PG8_LDA(dst, b, h) do { _Pragma("unroll") for (int m = 0; m < 4; ++m) _Pragma("unroll") for (int k = 0; k < 2; ++k) dst[m][k] = *(const LAS bf16x8*)(lds + PG8_SA(b, h) + aoff + m * 2048 + k * 1024); } while (0)
; #define PG8_MMA(ai, bj, At, Bt) do { __builtin_amdgcn_s_setprio(1); _Pragma("unroll") for (int m = 0; m < 4; ++m) _Pragma("unroll") for (int n = 0; n < 2; ++n) _Pragma("unroll") for (int k = 0; k < 2; ++k) \
;         acc[ai][bj][m][n] = __builtin_amdgcn_mfma_f32_16x16x32_bf16(Bt[n][k], At[m][k], acc[ai][bj][m][n], 0, 0, 0); __builtin_amdgcn_s_setprio(0); } while (0)
; #define PG8_WAIT_V(n) asm volatile("s_waitcnt vmcnt(" #n ")" ::: "memory")
; #define PG8_WAIT_L(n) asm volatile("s_waitcnt lgkmcnt(" #n ")" ::: "memory")
; #define PG8_BAR __builtin_amdgcn_s_barrier()
; #define PG8_SCHED __builtin_amdgcn_sched_barrier(0)
; template <class Epi>
; __device__ __forceinline__ void gemm_phase(LAS unsigned char* lds, const Gemm g, const StaticOrder& S, const Epi& E) {
;     ...
;             PG8_BAR; PG8_WAIT_L(0); PG8_MMA(0, 1, At, B1); PG8_BAR;
;             PG8_LDA(At, 1, 1); PG8_STAGE(PG8_SA(1, 0), a3, voffA);
;             PG8_BAR; PG8_WAIT_L(0); PG8_MMA(1, 0, At, B0); PG8_BAR; PG8_SCHED;
;             PG8_STAGE(PG8_SB(1, 1), b3 + hstep, voffB);
;             PG8_WAIT_V(6); PG8_BAR; PG8_MMA(1, 1, At, B1); PG8_BAR;
;         }
	s_waitcnt lgkmcnt(0)
	v_mfma_f32_16x16x32_bf16 v[70:73], v[206:209], v[160:163], v[70:73]
	v_mfma_f32_16x16x32_bf16 v[66:69], v[214:217], v[160:163], v[66:69]
	v_mfma_f32_16x16x32_bf16 v[54:57], v[206:209], v[168:171], v[54:57]
	v_mfma_f32_16x16x32_bf16 v[50:53], v[214:217], v[168:171], v[50:53]
	v_mfma_f32_16x16x32_bf16 v[46:49], v[206:209], v[190:193], v[46:49]
	v_mfma_f32_16x16x32_bf16 v[42:45], v[214:217], v[190:193], v[42:45]
	v_mfma_f32_16x16x32_bf16 v[38:41], v[206:209], v[198:201], v[38:41]
	v_mfma_f32_16x16x32_bf16 v[34:37], v[214:217], v[198:201], v[34:37]
	v_mfma_f32_16x16x32_bf16 v[70:73], v[210:213], v[164:167], v[70:73]
	v_mfma_f32_16x16x32_bf16 v[66:69], v[218:221], v[164:167], v[66:69]
	v_mfma_f32_16x16x32_bf16 v[54:57], v[210:213], v[172:175], v[54:57]
	v_mfma_f32_16x16x32_bf16 v[50:53], v[218:221], v[172:175], v[50:53]
	v_mfma_f32_16x16x32_bf16 v[46:49], v[210:213], v[194:197], v[46:49]
	v_mfma_f32_16x16x32_bf16 v[42:45], v[218:221], v[194:197], v[42:45]
	v_mfma_f32_16x16x32_bf16 v[38:41], v[210:213], v[202:205], v[38:41]
	v_mfma_f32_16x16x32_bf16 v[34:37], v[218:221], v[202:205], v[34:37]
	s_mov_b32 m0, s34
	v_lshl_add_u64 v[176:177], v[222:223], 0, s[86:87]
	s_barrier
	ds_read_b128 v[160:163], v143 offset:49152
	ds_read_b128 v[164:167], v143 offset:50176
	ds_read_b128 v[168:171], v143 offset:51200
	ds_read_b128 v[172:175], v143 offset:52224
	ds_read_b128 v[190:193], v143 offset:53248
	ds_read_b128 v[194:197], v143 offset:54272
	ds_read_b128 v[198:201], v143 offset:55296
	ds_read_b128 v[202:205], v143 offset:56320
	global_load_lds_dwordx4 v[176:177], off
	s_mov_b32 m0, s35
	v_lshl_add_u64 v[176:177], v[224:225], 0, s[86:87]
	global_load_lds_dwordx4 v[176:177], off
	s_barrier
	s_waitcnt lgkmcnt(0)
	v_mfma_f32_16x16x32_bf16 v[94:97], v[144:147], v[160:163], v[94:97]
	v_mfma_f32_16x16x32_bf16 v[90:93], v[152:155], v[160:163], v[90:93]
	v_mfma_f32_16x16x32_bf16 v[86:89], v[144:147], v[168:171], v[86:89]
	v_mfma_f32_16x16x32_bf16 v[82:85], v[152:155], v[168:171], v[82:85]
	v_mfma_f32_16x16x32_bf16 v[78:81], v[144:147], v[190:193], v[78:81]
	v_mfma_f32_16x16x32_bf16 v[74:77], v[152:155], v[190:193], v[74:77]
	v_mfma_f32_16x16x32_bf16 v[62:65], v[144:147], v[198:201], v[62:65]
	v_mfma_f32_16x16x32_bf16 v[58:61], v[152:155], v[198:201], v[58:61]
	v_mfma_f32_16x16x32_bf16 v[94:97], v[148:151], v[164:167], v[94:97]
	v_mfma_f32_16x16x32_bf16 v[90:93], v[156:159], v[164:167], v[90:93]
	v_mfma_f32_16x16x32_bf16 v[86:89], v[148:151], v[172:175], v[86:89]
	v_mfma_f32_16x16x32_bf16 v[82:85], v[156:159], v[172:175], v[82:85]
	v_mfma_f32_16x16x32_bf16 v[78:81], v[148:151], v[194:197], v[78:81]
	v_mfma_f32_16x16x32_bf16 v[74:77], v[156:159], v[194:197], v[74:77]
	v_mfma_f32_16x16x32_bf16 v[62:65], v[148:151], v[202:205], v[62:65]
	v_mfma_f32_16x16x32_bf16 v[58:61], v[156:159], v[202:205], v[58:61]
	s_barrier
	s_add_u32 s0, s18, 0x20080
	s_addc_u32 s1, s19, 0
	s_add_i32 s18, s20, s27
	s_mov_b32 m0, s18
	v_lshl_add_u64 v[144:145], s[0:1], 0, v[4:5]
	global_load_lds_dwordx4 v[144:145], off
	s_add_i32 m0, s18, 0x2000
	v_lshl_add_u64 v[144:145], s[0:1], 0, v[130:131]
	global_load_lds_dwordx4 v[144:145], off
	s_waitcnt vmcnt(6)
	s_barrier
	v_mfma_f32_16x16x32_bf16 v[30:33], v[206:209], v[160:163], v[30:33]
	v_mfma_f32_16x16x32_bf16 v[26:29], v[214:217], v[160:163], v[26:29]
	v_mfma_f32_16x16x32_bf16 v[22:25], v[206:209], v[168:171], v[22:25]
	v_mfma_f32_16x16x32_bf16 v[18:21], v[214:217], v[168:171], v[18:21]
	v_mfma_f32_16x16x32_bf16 v[14:17], v[206:209], v[190:193], v[14:17]
	v_mfma_f32_16x16x32_bf16 v[10:13], v[214:217], v[190:193], v[10:13]
	v_mfma_f32_16x16x32_bf16 v[6:9], v[206:209], v[198:201], v[6:9]
	v_mfma_f32_16x16x32_bf16 v[0:3], v[214:217], v[198:201], v[0:3]
	v_mfma_f32_16x16x32_bf16 v[30:33], v[210:213], v[164:167], v[30:33]
	v_mfma_f32_16x16x32_bf16 v[26:29], v[218:221], v[164:167], v[26:29]
	v_mfma_f32_16x16x32_bf16 v[22:25], v[210:213], v[172:175], v[22:25]
	v_mfma_f32_16x16x32_bf16 v[18:21], v[218:221], v[172:175], v[18:21]
	v_mfma_f32_16x16x32_bf16 v[14:17], v[210:213], v[194:197], v[14:17]
	v_mfma_f32_16x16x32_bf16 v[10:13], v[218:221], v[194:197], v[10:13]
	v_mfma_f32_16x16x32_bf16 v[6:9], v[210:213], v[202:205], v[6:9]
	v_mfma_f32_16x16x32_bf16 v[0:3], v[218:221], v[202:205], v[0:3]
	s_add_i32 s43, s43, 2
	s_add_u32 s16, s16, 0x100
	s_addc_u32 s17, s17, 0
	s_add_u32 s41, s41, 0x100
	s_addc_u32 s42, s42, 0
	s_cmp_gt_u32 s43, 5
	s_barrier
	s_cbranch_scc1 .Lpeel_exit_3
	.p2align 6

; #define PG8_STAGE(bufoff, gbase, voff) do { _Pragma("unroll") for (int _i = 0; _i < 2; ++_i) \
;         __builtin_amdgcn_global_load_lds((const unsigned*)((const char*)(gbase) + (voff)[_i]), (LAS unsigned*)(lds + (bufoff) + ldsw + _i * 8192), 16, 0, 0); } while (0)
; #define PG8_LDA(dst, b, h) do { _Pragma("unroll") for (int m = 0; m < 4; ++m) _Pragma("unroll") for (int k = 0; k < 2; ++k) dst[m][k] = *(const LAS bf16x8*)(lds + PG8_SA(b, h) + aoff + m * 2048 + k * 1024); } while (0)
; #define PG8_LDB(dst, b, h) do { _Pragma("unroll") for (int n = 0; n < 2; ++n) _Pragma("unroll") for (int k = 0; k < 2; ++k) dst[n][k] = *(const LAS bf16x8*)(lds + PG8_SB(b, h) + boff + n * 2048 + k * 1024); } while (0)
; #define PG8_MMA(ai, bj, At, Bt) do { __builtin_amdgcn_s_setprio(1); _Pragma("unroll") for (int m = 0; m < 4; ++m) _Pragma("unroll") for (int n = 0; n < 2; ++n) _Pragma("unroll") for (int k = 0; k < 2; ++k) \
;         acc[ai][bj][m][n] = __builtin_amdgcn_mfma_f32_16x16x32_bf16(Bt[n][k], At[m][k], acc[ai][bj][m][n], 0, 0, 0); __builtin_amdgcn_s_setprio(0); } while (0)
; #define PG8_WAIT_V(n) asm volatile("s_waitcnt vmcnt(" #n ")" ::: "memory")
; #define PG8_WAIT_L(n) asm volatile("s_waitcnt lgkmcnt(" #n ")" ::: "memory")
; #define PG8_BAR __builtin_amdgcn_s_barrier()
; template <class Epi>
; __device__ __forceinline__ void gemm_phase(LAS unsigned char* lds, const Gemm g, const StaticOrder& S, const Epi& E) {
;     ...
;             const bool last = (t == nt - 2);
;             const char* a1 = cA + (size_t)(t + 1) * kstep;
;             const char* a2 = last ? nA : cA + (size_t)(t + 2) * kstep; const char* b2 = last ? nB : cB + (size_t)(t + 2) * kstep;
;             const char* a3 = a2 + kstep; const char* b3 = b2 + kstep;
;             PG8_LDB(B0, 0, 0); PG8_SCHED; PG8_LDA(At, 0, 0); PG8_STAGE(PG8_SA(1, 1), a1 + hstep, voffA);
;             PG8_WAIT_L(8); PG8_BAR; PG8_WAIT_L(0); PG8_MMA(0, 0, At, B0); PG8_BAR; PG8_SCHED;
;             PG8_LDB(B1, 0, 1); PG8_STAGE(PG8_SB(0, 0), b2, voffB);
;             PG8_BAR; PG8_WAIT_L(0); PG8_MMA(0, 1, At, B1); PG8_BAR;
;             PG8_LDA(At, 0, 1); PG8_STAGE(PG8_SA(0, 0), a2, voffA);
;             PG8_BAR; PG8_WAIT_L(0); PG8_MMA(1, 0, At, B0); PG8_BAR; PG8_SCHED;
;             PG8_STAGE(PG8_SB(0, 1), b2 + hstep, voffB);
;             PG8_WAIT_V(6); PG8_BAR; PG8_MMA(1, 1, At, B1); PG8_BAR;
.Lsp_skip_2:
	s_add_u32 s0, s6, 0xfffc0080
	s_addc_u32 s1, s7, -1
	s_add_i32 s55, 0, 0x10000
	v_add_u32_e32 v130, s55, v243
	ds_read_b128 v[34:37], v130
	ds_read_b128 v[38:41], v130 offset:1024
	ds_read_b128 v[122:125], v130 offset:2048
	ds_read_b128 v[130:133], v130 offset:3072
	s_cmp_eq_u32 s54, 12
	s_cselect_b32 s25, s17, s1
	s_cselect_b32 s24, s49, s0
	s_cselect_b32 s23, s15, s52
	s_cselect_b32 s22, s50, s51
	v_lshl_add_u64 v[186:187], s[6:7], 0, v[196:197]
	s_add_i32 m0, s34, 0xc000
	ds_read_b128 v[146:149], v245
	ds_read_b128 v[150:153], v245 offset:1024
	ds_read_b128 v[154:157], v245 offset:2048
	ds_read_b128 v[158:161], v245 offset:3072
	ds_read_b128 v[162:165], v245 offset:4096
	ds_read_b128 v[166:169], v245 offset:5120
	ds_read_b128 v[170:173], v245 offset:6144
	ds_read_b128 v[174:177], v245 offset:7168
	global_load_lds_dwordx4 v[186:187], off
	s_add_i32 m0, s34, 0xe000
	v_lshl_add_u64 v[186:187], s[6:7], 0, v[198:199]
	global_load_lds_dwordx4 v[186:187], off
	s_waitcnt lgkmcnt(8)
	s_barrier
	s_waitcnt lgkmcnt(0)
	v_mfma_f32_16x16x32_bf16 v[142:145], v[34:37], v[146:149], 0
	v_mfma_f32_16x16x32_bf16 v[138:141], v[122:125], v[146:149], 0
	v_mfma_f32_16x16x32_bf16 v[134:137], v[34:37], v[154:157], 0
	v_mfma_f32_16x16x32_bf16 v[126:129], v[122:125], v[154:157], 0
	v_mfma_f32_16x16x32_bf16 v[118:121], v[34:37], v[162:165], 0
	v_mfma_f32_16x16x32_bf16 v[114:117], v[122:125], v[162:165], 0
	v_mfma_f32_16x16x32_bf16 v[110:113], v[34:37], v[170:173], 0
	v_mfma_f32_16x16x32_bf16 v[106:109], v[122:125], v[170:173], 0
	v_mfma_f32_16x16x32_bf16 v[142:145], v[38:41], v[150:153], v[142:145]
	v_mfma_f32_16x16x32_bf16 v[138:141], v[130:133], v[150:153], v[138:141]
	v_mfma_f32_16x16x32_bf16 v[134:137], v[38:41], v[158:161], v[134:137]
	v_mfma_f32_16x16x32_bf16 v[126:129], v[130:133], v[158:161], v[126:129]
	v_mfma_f32_16x16x32_bf16 v[118:121], v[38:41], v[166:169], v[118:121]
	v_mfma_f32_16x16x32_bf16 v[114:117], v[130:133], v[166:169], v[114:117]
	v_mfma_f32_16x16x32_bf16 v[110:113], v[38:41], v[174:177], v[110:113]
	v_mfma_f32_16x16x32_bf16 v[106:109], v[130:133], v[174:177], v[106:109]
	s_barrier
	s_add_i32 s56, 0, 0x14000
	v_add_u32_e32 v186, s56, v243
	s_add_i32 s0, s55, s31
	ds_read_b128 v[200:203], v186
	ds_read_b128 v[204:207], v186 offset:1024
	ds_read_b128 v[208:211], v186 offset:2048
	ds_read_b128 v[212:215], v186 offset:3072
	v_lshl_add_u64 v[186:187], s[22:23], 0, v[4:5]
	s_mov_b32 m0, s0
	v_lshl_add_u64 v[216:217], s[22:23], 0, v[190:191]
	global_load_lds_dwordx4 v[186:187], off
	s_add_i32 m0, s0, 0x2000
	s_nop 0
	global_load_lds_dwordx4 v[216:217], off
	s_barrier
	s_waitcnt lgkmcnt(0)
	v_mfma_f32_16x16x32_bf16 v[70:73], v[200:203], v[146:149], 0
	v_mfma_f32_16x16x32_bf16 v[66:69], v[208:211], v[146:149], 0
	v_mfma_f32_16x16x32_bf16 v[62:65], v[200:203], v[154:157], 0
	v_mfma_f32_16x16x32_bf16 v[58:61], v[208:211], v[154:157], 0
	v_mfma_f32_16x16x32_bf16 v[54:57], v[200:203], v[162:165], 0
	v_mfma_f32_16x16x32_bf16 v[50:53], v[208:211], v[162:165], 0
	v_mfma_f32_16x16x32_bf16 v[46:49], v[200:203], v[170:173], 0
	v_mfma_f32_16x16x32_bf16 v[42:45], v[208:211], v[170:173], 0
	v_mfma_f32_16x16x32_bf16 v[70:73], v[204:207], v[150:153], v[70:73]
	v_mfma_f32_16x16x32_bf16 v[66:69], v[212:215], v[150:153], v[66:69]
	v_mfma_f32_16x16x32_bf16 v[62:65], v[204:207], v[158:161], v[62:65]
	v_mfma_f32_16x16x32_bf16 v[58:61], v[212:215], v[158:161], v[58:61]
	v_mfma_f32_16x16x32_bf16 v[54:57], v[204:207], v[166:169], v[54:57]
	v_mfma_f32_16x16x32_bf16 v[50:53], v[212:215], v[166:169], v[50:53]
	v_mfma_f32_16x16x32_bf16 v[46:49], v[204:207], v[174:177], v[46:49]
	v_mfma_f32_16x16x32_bf16 v[42:45], v[212:215], v[174:177], v[42:45]
	s_mov_b32 m0, s34
	v_lshl_add_u64 v[218:219], s[24:25], 0, v[194:195]
	s_barrier
	ds_read_b128 v[146:149], v245 offset:16384
	ds_read_b128 v[150:153], v245 offset:17408
	ds_read_b128 v[154:157], v245 offset:18432
	ds_read_b128 v[158:161], v245 offset:19456
	ds_read_b128 v[162:165], v245 offset:20480
	ds_read_b128 v[166:169], v245 offset:21504
	ds_read_b128 v[170:173], v245 offset:22528
	ds_read_b128 v[174:177], v245 offset:23552
	global_load_lds_dwordx4 v[218:219], off
	s_mov_b32 m0, s35
	v_lshl_add_u64 v[220:221], s[24:25], 0, v[192:193]
	global_load_lds_dwordx4 v[220:221], off
	s_barrier
	s_waitcnt lgkmcnt(0)
	v_mfma_f32_16x16x32_bf16 v[102:105], v[34:37], v[146:149], 0
	v_mfma_f32_16x16x32_bf16 v[98:101], v[122:125], v[146:149], 0
	v_mfma_f32_16x16x32_bf16 v[94:97], v[34:37], v[154:157], 0
	v_mfma_f32_16x16x32_bf16 v[90:93], v[122:125], v[154:157], 0
	v_mfma_f32_16x16x32_bf16 v[86:89], v[34:37], v[162:165], 0
	v_mfma_f32_16x16x32_bf16 v[82:85], v[122:125], v[162:165], 0
	v_mfma_f32_16x16x32_bf16 v[34:37], v[34:37], v[170:173], 0
	v_mfma_f32_16x16x32_bf16 v[102:105], v[38:41], v[150:153], v[102:105]
	v_mfma_f32_16x16x32_bf16 v[98:101], v[130:133], v[150:153], v[98:101]
	v_mfma_f32_16x16x32_bf16 v[94:97], v[38:41], v[158:161], v[94:97]
	v_mfma_f32_16x16x32_bf16 v[90:93], v[130:133], v[158:161], v[90:93]
	v_mfma_f32_16x16x32_bf16 v[86:89], v[38:41], v[166:169], v[86:89]
	v_mfma_f32_16x16x32_bf16 v[82:85], v[130:133], v[166:169], v[82:85]
	v_mfma_f32_16x16x32_bf16 v[34:37], v[38:41], v[174:177], v[34:37]
	v_mfma_f32_16x16x32_bf16 v[38:41], v[122:125], v[170:173], 0
	v_mfma_f32_16x16x32_bf16 v[38:41], v[130:133], v[174:177], v[38:41]
	s_barrier
	s_add_u32 s0, s22, 0x40000
	s_addc_u32 s1, s23, 0
	s_add_i32 s55, s56, s31
	s_mov_b32 m0, s55
	v_lshl_add_u64 v[74:75], s[0:1], 0, v[4:5]
	global_load_lds_dwordx4 v[74:75], off
	s_add_i32 m0, s55, 0x2000
	v_lshl_add_u64 v[74:75], s[0:1], 0, v[190:191]
	global_load_lds_dwordx4 v[74:75], off
	s_waitcnt vmcnt(6)
	s_barrier
; #define PG8_STAGE(bufoff, gbase, voff) do { _Pragma("unroll") for (int _i = 0; _i < 2; ++_i) \
;         __builtin_amdgcn_global_load_lds((const unsigned*)((const char*)(gbase) + (voff)[_i]), (LAS unsigned*)(lds + (bufoff) + ldsw + _i * 8192), 16, 0, 0); } while (0)
; #define PG8_LDA(dst, b, h) do { _Pragma("unroll") for (int m = 0; m < 4; ++m) _Pragma("unroll") for (int k = 0; k < 2; ++k) dst[m][k] = *(const LAS bf16x8*)(lds + PG8_SA(b, h) + aoff + m * 2048 + k * 1024); } while (0)
; #define PG8_LDB(dst, b, h) do { _Pragma("unroll") for (int n = 0; n < 2; ++n) _Pragma("unroll") for (int k = 0; k < 2; ++k) dst[n][k] = *(const LAS bf16x8*)(lds + PG8_SB(b, h) + boff + n * 2048 + k * 1024); } while (0)
; #define PG8_MMA(ai, bj, At, Bt) do { __builtin_amdgcn_s_setprio(1); _Pragma("unroll") for (int m = 0; m < 4; ++m) _Pragma("unroll") for (int n = 0; n < 2; ++n) _Pragma("unroll") for (int k = 0; k < 2; ++k) \
;         acc[ai][bj][m][n] = __builtin_amdgcn_mfma_f32_16x16x32_bf16(Bt[n][k], At[m][k], acc[ai][bj][m][n], 0, 0, 0); __builtin_amdgcn_s_setprio(0); } while (0)
; #define PG8_WAIT_V(n) asm volatile("s_waitcnt vmcnt(" #n ")" ::: "memory")
; #define PG8_WAIT_L(n) asm volatile("s_waitcnt lgkmcnt(" #n ")" ::: "memory")
; #define PG8_BAR __builtin_amdgcn_s_barrier()
; #define PG8_SCHED __builtin_amdgcn_sched_barrier(0)
; template <class Epi>
; __device__ __forceinline__ void gemm_phase(LAS unsigned char* lds, const Gemm g, const StaticOrder& S, const Epi& E) {
;     ...
;             PG8_WAIT_V(6); PG8_BAR; PG8_MMA(1, 1, At, B1); PG8_BAR;
;             PG8_LDB(B0, 1, 0); PG8_SCHED; PG8_LDA(At, 1, 0); PG8_STAGE(PG8_SA(0, 1), a2 + hstep, voffA);
;             PG8_WAIT_L(8); PG8_BAR; PG8_WAIT_L(0); PG8_MMA(0, 0, At, B0); PG8_BAR; PG8_SCHED;
;             PG8_LDB(B1, 1, 1); PG8_STAGE(PG8_SB(1, 0), b3, voffB);
;             PG8_BAR; PG8_WAIT_L(0); PG8_MMA(0, 1, At, B1); PG8_BAR;
	v_mfma_f32_16x16x32_bf16 v[30:33], v[200:203], v[146:149], 0
	v_mfma_f32_16x16x32_bf16 v[26:29], v[208:211], v[146:149], 0
	v_mfma_f32_16x16x32_bf16 v[22:25], v[200:203], v[154:157], 0
	v_mfma_f32_16x16x32_bf16 v[18:21], v[208:211], v[154:157], 0
	v_mfma_f32_16x16x32_bf16 v[14:17], v[200:203], v[162:165], 0
	v_mfma_f32_16x16x32_bf16 v[10:13], v[208:211], v[162:165], 0
	v_mfma_f32_16x16x32_bf16 v[6:9], v[200:203], v[170:173], 0
	v_mfma_f32_16x16x32_bf16 v[0:3], v[208:211], v[170:173], 0
	v_mfma_f32_16x16x32_bf16 v[30:33], v[204:207], v[150:153], v[30:33]
	v_mfma_f32_16x16x32_bf16 v[26:29], v[212:215], v[150:153], v[26:29]
	v_mfma_f32_16x16x32_bf16 v[22:25], v[204:207], v[158:161], v[22:25]
	v_mfma_f32_16x16x32_bf16 v[18:21], v[212:215], v[158:161], v[18:21]
	v_mfma_f32_16x16x32_bf16 v[14:17], v[204:207], v[166:169], v[14:17]
	v_mfma_f32_16x16x32_bf16 v[10:13], v[212:215], v[166:169], v[10:13]
	v_mfma_f32_16x16x32_bf16 v[6:9], v[204:207], v[174:177], v[6:9]
	v_mfma_f32_16x16x32_bf16 v[0:3], v[212:215], v[174:177], v[0:3]
	s_add_i32 s55, 0, 0x18000
	v_add_u32_e32 v130, s55, v243
	s_barrier
	ds_read_b128 v[74:77], v130
	ds_read_b128 v[78:81], v130 offset:1024
	ds_read_b128 v[122:125], v130 offset:2048
	ds_read_b128 v[130:133], v130 offset:3072
	s_add_u32 s0, s24, 0x40000
	s_addc_u32 s1, s25, 0
	s_mov_b32 m0, s36
	v_lshl_add_u64 v[200:201], s[0:1], 0, v[194:195]
	ds_read_b128 v[146:149], v245 offset:32768
	ds_read_b128 v[150:153], v245 offset:33792
	ds_read_b128 v[154:157], v245 offset:34816
	ds_read_b128 v[158:161], v245 offset:35840
	ds_read_b128 v[162:165], v245 offset:36864
	ds_read_b128 v[166:169], v245 offset:37888
	ds_read_b128 v[170:173], v245 offset:38912
	ds_read_b128 v[174:177], v245 offset:39936
	global_load_lds_dwordx4 v[200:201], off
	s_mov_b32 m0, s37
	v_lshl_add_u64 v[200:201], s[0:1], 0, v[192:193]
	global_load_lds_dwordx4 v[200:201], off
	s_waitcnt lgkmcnt(8)
	s_barrier
	s_waitcnt lgkmcnt(0)
	v_mfma_f32_16x16x32_bf16 v[142:145], v[74:77], v[146:149], v[142:145]
	v_mfma_f32_16x16x32_bf16 v[138:141], v[122:125], v[146:149], v[138:141]
	v_mfma_f32_16x16x32_bf16 v[134:137], v[74:77], v[154:157], v[134:137]
	v_mfma_f32_16x16x32_bf16 v[126:129], v[122:125], v[154:157], v[126:129]
	v_mfma_f32_16x16x32_bf16 v[118:121], v[74:77], v[162:165], v[118:121]
	v_mfma_f32_16x16x32_bf16 v[114:117], v[122:125], v[162:165], v[114:117]
	v_mfma_f32_16x16x32_bf16 v[110:113], v[74:77], v[170:173], v[110:113]
	v_mfma_f32_16x16x32_bf16 v[106:109], v[122:125], v[170:173], v[106:109]
	v_mfma_f32_16x16x32_bf16 v[142:145], v[78:81], v[150:153], v[142:145]
	v_mfma_f32_16x16x32_bf16 v[138:141], v[130:133], v[150:153], v[138:141]
	v_mfma_f32_16x16x32_bf16 v[134:137], v[78:81], v[158:161], v[134:137]
	v_mfma_f32_16x16x32_bf16 v[126:129], v[130:133], v[158:161], v[126:129]
	v_mfma_f32_16x16x32_bf16 v[118:121], v[78:81], v[166:169], v[118:121]
	v_mfma_f32_16x16x32_bf16 v[114:117], v[130:133], v[166:169], v[114:117]
	v_mfma_f32_16x16x32_bf16 v[110:113], v[78:81], v[174:177], v[110:113]
	v_mfma_f32_16x16x32_bf16 v[106:109], v[130:133], v[174:177], v[106:109]
	s_barrier
	s_add_i32 s24, 0, 0x1c000
	s_add_i32 s0, s55, s31
	v_add_u32_e32 v212, s24, v243
	v_lshl_add_u64 v[186:187], v[186:187], 0, s[86:87]
	s_mov_b32 m0, s0
	ds_read_b128 v[200:203], v212
	ds_read_b128 v[204:207], v212 offset:1024
	ds_read_b128 v[208:211], v212 offset:2048
	ds_read_b128 v[212:215], v212 offset:3072
	global_load_lds_dwordx4 v[186:187], off
	s_add_i32 m0, s0, 0x2000
	v_lshl_add_u64 v[186:187], v[216:217], 0, s[86:87]
	global_load_lds_dwordx4 v[186:187], off
	s_barrier
; #define PG8_STAGE(bufoff, gbase, voff) do { _Pragma("unroll") for (int _i = 0; _i < 2; ++_i) \
;         __builtin_amdgcn_global_load_lds((const unsigned*)((const char*)(gbase) + (voff)[_i]), (LAS unsigned*)(lds + (bufoff) + ldsw + _i * 8192), 16, 0, 0); } while (0)
; #define PG8_LDA(dst, b, h) do { _Pragma("unroll") for (int m = 0; m < 4; ++m) _Pragma("unroll") for (int k = 0; k < 2; ++k) dst[m][k] = *(const LAS bf16x8*)(lds + PG8_SA(b, h) + aoff + m * 2048 + k * 1024); } while (0)
; #define PG8_MMA(ai, bj, At, Bt) do { __builtin_amdgcn_s_setprio(1); _Pragma("unroll") for (int m = 0; m < 4; ++m) _Pragma("unroll") for (int n = 0; n < 2; ++n) _Pragma("unroll") for (int k = 0; k < 2; ++k) \
;         acc[ai][bj][m][n] = __builtin_amdgcn_mfma_f32_16x16x32_bf16(Bt[n][k], At[m][k], acc[ai][bj][m][n], 0, 0, 0); __builtin_amdgcn_s_setprio(0); } while (0)
; #define PG8_WAIT_V(n) asm volatile("s_waitcnt vmcnt(" #n ")" ::: "memory")
; #define PG8_WAIT_L(n) asm volatile("s_waitcnt lgkmcnt(" #n ")" ::: "memory")
; #define PG8_BAR __builtin_amdgcn_s_barrier()
; #define PG8_SCHED __builtin_amdgcn_sched_barrier(0)
; template <class Epi>
; __device__ __forceinline__ void gemm_phase(LAS unsigned char* lds, const Gemm g, const StaticOrder& S, const Epi& E) {
;     ...
;             PG8_BAR; PG8_WAIT_L(0); PG8_MMA(0, 1, At, B1); PG8_BAR;
;             PG8_LDA(At, 1, 1); PG8_STAGE(PG8_SA(1, 0), a3, voffA);
;             PG8_BAR; PG8_WAIT_L(0); PG8_MMA(1, 0, At, B0); PG8_BAR; PG8_SCHED;
;             PG8_STAGE(PG8_SB(1, 1), b3 + hstep, voffB);
;             PG8_WAIT_V(6); PG8_BAR; PG8_MMA(1, 1, At, B1); PG8_BAR;
;         }
	s_waitcnt lgkmcnt(0)
	v_mfma_f32_16x16x32_bf16 v[70:73], v[200:203], v[146:149], v[70:73]
	v_mfma_f32_16x16x32_bf16 v[66:69], v[208:211], v[146:149], v[66:69]
	v_mfma_f32_16x16x32_bf16 v[62:65], v[200:203], v[154:157], v[62:65]
	v_mfma_f32_16x16x32_bf16 v[58:61], v[208:211], v[154:157], v[58:61]
	v_mfma_f32_16x16x32_bf16 v[54:57], v[200:203], v[162:165], v[54:57]
	v_mfma_f32_16x16x32_bf16 v[50:53], v[208:211], v[162:165], v[50:53]
	v_mfma_f32_16x16x32_bf16 v[46:49], v[200:203], v[170:173], v[46:49]
	v_mfma_f32_16x16x32_bf16 v[42:45], v[208:211], v[170:173], v[42:45]
	v_mfma_f32_16x16x32_bf16 v[70:73], v[204:207], v[150:153], v[70:73]
	v_mfma_f32_16x16x32_bf16 v[66:69], v[212:215], v[150:153], v[66:69]
	v_mfma_f32_16x16x32_bf16 v[62:65], v[204:207], v[158:161], v[62:65]
	v_mfma_f32_16x16x32_bf16 v[58:61], v[212:215], v[158:161], v[58:61]
	v_mfma_f32_16x16x32_bf16 v[54:57], v[204:207], v[166:169], v[54:57]
	v_mfma_f32_16x16x32_bf16 v[50:53], v[212:215], v[166:169], v[50:53]
	v_mfma_f32_16x16x32_bf16 v[46:49], v[204:207], v[174:177], v[46:49]
	v_mfma_f32_16x16x32_bf16 v[42:45], v[212:215], v[174:177], v[42:45]
	s_mov_b32 m0, s40
	v_lshl_add_u64 v[186:187], v[218:219], 0, s[86:87]
	s_barrier
	ds_read_b128 v[146:149], v245 offset:49152
	ds_read_b128 v[150:153], v245 offset:50176
	ds_read_b128 v[154:157], v245 offset:51200
	ds_read_b128 v[158:161], v245 offset:52224
	ds_read_b128 v[162:165], v245 offset:53248
	ds_read_b128 v[166:169], v245 offset:54272
	ds_read_b128 v[170:173], v245 offset:55296
	ds_read_b128 v[174:177], v245 offset:56320
	global_load_lds_dwordx4 v[186:187], off
	s_mov_b32 m0, s41
	v_lshl_add_u64 v[186:187], v[220:221], 0, s[86:87]
	global_load_lds_dwordx4 v[186:187], off
	s_barrier
	s_waitcnt lgkmcnt(0)
	v_mfma_f32_16x16x32_bf16 v[102:105], v[74:77], v[146:149], v[102:105]
	v_mfma_f32_16x16x32_bf16 v[94:97], v[74:77], v[154:157], v[94:97]
	v_mfma_f32_16x16x32_bf16 v[86:89], v[74:77], v[162:165], v[86:89]
	v_mfma_f32_16x16x32_bf16 v[34:37], v[74:77], v[170:173], v[34:37]
	v_mfma_f32_16x16x32_bf16 v[102:105], v[78:81], v[150:153], v[102:105]
	v_mfma_f32_16x16x32_bf16 v[98:101], v[122:125], v[146:149], v[98:101]
	v_mfma_f32_16x16x32_bf16 v[94:97], v[78:81], v[158:161], v[94:97]
	v_mfma_f32_16x16x32_bf16 v[90:93], v[122:125], v[154:157], v[90:93]
	v_mfma_f32_16x16x32_bf16 v[86:89], v[78:81], v[166:169], v[86:89]
	v_mfma_f32_16x16x32_bf16 v[82:85], v[122:125], v[162:165], v[82:85]
	v_mfma_f32_16x16x32_bf16 v[78:81], v[78:81], v[174:177], v[34:37]
	v_mfma_f32_16x16x32_bf16 v[34:37], v[122:125], v[170:173], v[38:41]
	v_mfma_f32_16x16x32_bf16 v[98:101], v[130:133], v[150:153], v[98:101]
	v_mfma_f32_16x16x32_bf16 v[90:93], v[130:133], v[158:161], v[90:93]
	v_mfma_f32_16x16x32_bf16 v[82:85], v[130:133], v[166:169], v[82:85]
	v_mfma_f32_16x16x32_bf16 v[74:77], v[130:133], v[174:177], v[34:37]
	s_barrier
	s_add_u32 s0, s22, 0x40080
	s_addc_u32 s1, s23, 0
	s_add_i32 s22, s24, s31
	s_mov_b32 m0, s22
	v_lshl_add_u64 v[34:35], s[0:1], 0, v[4:5]
	global_load_lds_dwordx4 v[34:35], off
	s_add_i32 m0, s22, 0x2000
	v_lshl_add_u64 v[34:35], s[0:1], 0, v[190:191]
	global_load_lds_dwordx4 v[34:35], off
	s_waitcnt vmcnt(6)
	s_barrier
	v_mfma_f32_16x16x32_bf16 v[30:33], v[200:203], v[146:149], v[30:33]
	v_mfma_f32_16x16x32_bf16 v[26:29], v[208:211], v[146:149], v[26:29]
	v_mfma_f32_16x16x32_bf16 v[22:25], v[200:203], v[154:157], v[22:25]
	v_mfma_f32_16x16x32_bf16 v[18:21], v[208:211], v[154:157], v[18:21]
	v_mfma_f32_16x16x32_bf16 v[14:17], v[200:203], v[162:165], v[14:17]
	v_mfma_f32_16x16x32_bf16 v[10:13], v[208:211], v[162:165], v[10:13]
	v_mfma_f32_16x16x32_bf16 v[6:9], v[200:203], v[170:173], v[6:9]
	v_mfma_f32_16x16x32_bf16 v[0:3], v[208:211], v[170:173], v[0:3]
	v_mfma_f32_16x16x32_bf16 v[30:33], v[204:207], v[150:153], v[30:33]
	v_mfma_f32_16x16x32_bf16 v[26:29], v[212:215], v[150:153], v[26:29]
	v_mfma_f32_16x16x32_bf16 v[22:25], v[204:207], v[158:161], v[22:25]
	v_mfma_f32_16x16x32_bf16 v[18:21], v[212:215], v[158:161], v[18:21]
	v_mfma_f32_16x16x32_bf16 v[14:17], v[204:207], v[166:169], v[14:17]
	v_mfma_f32_16x16x32_bf16 v[10:13], v[212:215], v[166:169], v[10:13]
	v_mfma_f32_16x16x32_bf16 v[6:9], v[204:207], v[174:177], v[6:9]
	v_mfma_f32_16x16x32_bf16 v[0:3], v[212:215], v[174:177], v[0:3]
	s_add_i32 s54, s54, 2
	s_add_u32 s6, s6, 0x100
	s_addc_u32 s7, s7, 0
	s_add_u32 s51, s51, 0x100
	s_addc_u32 s52, s52, 0
	s_cmp_gt_u32 s54, 13
	s_barrier
	s_cbranch_scc1 .Lpeel_exit_2
	.p2align 6

; #define PG8_STAGE(bufoff, gbase, voff) do { _Pragma("unroll") for (int _i = 0; _i < 2; ++_i) \
;         __builtin_amdgcn_global_load_lds((const unsigned*)((const char*)(gbase) + (voff)[_i]), (LAS unsigned*)(lds + (bufoff) + ldsw + _i * 8192), 16, 0, 0); } while (0)
; #define PG8_LDA(dst, b, h) do { _Pragma("unroll") for (int m = 0; m < 4; ++m) _Pragma("unroll") for (int k = 0; k < 2; ++k) dst[m][k] = *(const LAS bf16x8*)(lds + PG8_SA(b, h) + aoff + m * 2048 + k * 1024); } while (0)
; #define PG8_LDB(dst, b, h) do { _Pragma("unroll") for (int n = 0; n < 2; ++n) _Pragma("unroll") for (int k = 0; k < 2; ++k) dst[n][k] = *(const LAS bf16x8*)(lds + PG8_SB(b, h) + boff + n * 2048 + k * 1024); } while (0)
; #define PG8_MMA(ai, bj, At, Bt) do { __builtin_amdgcn_s_setprio(1); _Pragma("unroll") for (int m = 0; m < 4; ++m) _Pragma("unroll") for (int n = 0; n < 2; ++n) _Pragma("unroll") for (int k = 0; k < 2; ++k) \
;         acc[ai][bj][m][n] = __builtin_amdgcn_mfma_f32_16x16x32_bf16(Bt[n][k], At[m][k], acc[ai][bj][m][n], 0, 0, 0); __builtin_amdgcn_s_setprio(0); } while (0)
; #define PG8_WAIT_V(n) asm volatile("s_waitcnt vmcnt(" #n ")" ::: "memory")
; #define PG8_WAIT_L(n) asm volatile("s_waitcnt lgkmcnt(" #n ")" ::: "memory")
; #define PG8_BAR __builtin_amdgcn_s_barrier()
; template <class Epi>
; __device__ __forceinline__ void gemm_phase(LAS unsigned char* lds, const Gemm g, const StaticOrder& S, const Epi& E) {
;     ...
;             const bool last = (t == nt - 2);
;             const char* a1 = cA + (size_t)(t + 1) * kstep;
;             const char* a2 = last ? nA : cA + (size_t)(t + 2) * kstep; const char* b2 = last ? nB : cB + (size_t)(t + 2) * kstep;
;             const char* a3 = a2 + kstep; const char* b3 = b2 + kstep;
;             PG8_LDB(B0, 0, 0); PG8_SCHED; PG8_LDA(At, 0, 0); PG8_STAGE(PG8_SA(1, 1), a1 + hstep, voffA);
;             PG8_WAIT_L(8); PG8_BAR; PG8_WAIT_L(0); PG8_MMA(0, 0, At, B0); PG8_BAR; PG8_SCHED;
;             PG8_LDB(B1, 0, 1); PG8_STAGE(PG8_SB(0, 0), b2, voffB);
;             PG8_BAR; PG8_WAIT_L(0); PG8_MMA(0, 1, At, B1); PG8_BAR;
;             PG8_LDA(At, 0, 1); PG8_STAGE(PG8_SA(0, 0), a2, voffA);
;             PG8_BAR; PG8_WAIT_L(0); PG8_MMA(1, 0, At, B0); PG8_BAR; PG8_SCHED;
;             PG8_STAGE(PG8_SB(0, 1), b2 + hstep, voffB);
;             PG8_WAIT_V(6); PG8_BAR; PG8_MMA(1, 1, At, B1); PG8_BAR;
.Lsp_skip_1:
	s_add_u32 s0, s18, 0xfffc0080
	s_addc_u32 s1, s19, -1
	s_add_i32 s54, 0, 0x10000
	v_add_u32_e32 v78, s54, v161
	ds_read_b128 v[66:69], v78
	ds_read_b128 v[70:73], v78 offset:1024
	ds_read_b128 v[74:77], v78 offset:2048
	ds_read_b128 v[78:81], v78 offset:3072
	s_cmp_eq_u32 s52, 12
	s_cselect_b32 s23, s13, s1
	s_cselect_b32 s22, s48, s0
	s_cselect_b32 s21, s11, s51
	s_cselect_b32 s20, s49, s50
	v_lshl_add_u64 v[156:157], s[18:19], 0, v[152:153]
	s_add_i32 m0, s30, 0xc000
	ds_read_b128 v[168:171], v165
	ds_read_b128 v[172:175], v165 offset:1024
	ds_read_b128 v[190:193], v165 offset:2048
	ds_read_b128 v[194:197], v165 offset:3072
	ds_read_b128 v[198:201], v165 offset:4096
	ds_read_b128 v[202:205], v165 offset:5120
	ds_read_b128 v[206:209], v165 offset:6144
	ds_read_b128 v[210:213], v165 offset:7168
	global_load_lds_dwordx4 v[156:157], off
	s_add_i32 m0, s30, 0xe000
	v_lshl_add_u64 v[156:157], s[18:19], 0, v[154:155]
	global_load_lds_dwordx4 v[156:157], off
	s_waitcnt lgkmcnt(8)
	s_barrier
	s_waitcnt lgkmcnt(0)
	v_mfma_f32_16x16x32_bf16 v[142:145], v[66:69], v[168:171], 0
	v_mfma_f32_16x16x32_bf16 v[138:141], v[74:77], v[168:171], 0
	v_mfma_f32_16x16x32_bf16 v[126:129], v[66:69], v[190:193], 0
	v_mfma_f32_16x16x32_bf16 v[122:125], v[74:77], v[190:193], 0
	v_mfma_f32_16x16x32_bf16 v[110:113], v[66:69], v[198:201], 0
	v_mfma_f32_16x16x32_bf16 v[106:109], v[74:77], v[198:201], 0
	v_mfma_f32_16x16x32_bf16 v[94:97], v[66:69], v[206:209], 0
	v_mfma_f32_16x16x32_bf16 v[90:93], v[74:77], v[206:209], 0
	v_mfma_f32_16x16x32_bf16 v[142:145], v[70:73], v[172:175], v[142:145]
	v_mfma_f32_16x16x32_bf16 v[138:141], v[78:81], v[172:175], v[138:141]
	v_mfma_f32_16x16x32_bf16 v[126:129], v[70:73], v[194:197], v[126:129]
	v_mfma_f32_16x16x32_bf16 v[122:125], v[78:81], v[194:197], v[122:125]
	v_mfma_f32_16x16x32_bf16 v[110:113], v[70:73], v[202:205], v[110:113]
	v_mfma_f32_16x16x32_bf16 v[106:109], v[78:81], v[202:205], v[106:109]
	v_mfma_f32_16x16x32_bf16 v[94:97], v[70:73], v[210:213], v[94:97]
	v_mfma_f32_16x16x32_bf16 v[90:93], v[78:81], v[210:213], v[90:93]
	s_barrier
	s_add_i32 s0, 0, 0x14000
	v_add_u32_e32 v156, s0, v161
	s_add_i32 s1, s54, s29
	ds_read_b128 v[214:217], v156
	ds_read_b128 v[218:221], v156 offset:1024
	ds_read_b128 v[222:225], v156 offset:2048
	ds_read_b128 v[242:245], v156 offset:3072
	v_lshl_add_u64 v[156:157], s[20:21], 0, v[4:5]
	s_mov_b32 m0, s1
	v_lshl_add_u64 v[176:177], s[20:21], 0, v[146:147]
	global_load_lds_dwordx4 v[156:157], off
	s_add_i32 m0, s1, 0x2000
	s_nop 0
	global_load_lds_dwordx4 v[176:177], off
	s_barrier
	s_waitcnt lgkmcnt(0)
	v_mfma_f32_16x16x32_bf16 v[134:137], v[214:217], v[168:171], 0
	v_mfma_f32_16x16x32_bf16 v[130:133], v[222:225], v[168:171], 0
	v_mfma_f32_16x16x32_bf16 v[118:121], v[214:217], v[190:193], 0
	v_mfma_f32_16x16x32_bf16 v[114:117], v[222:225], v[190:193], 0
	v_mfma_f32_16x16x32_bf16 v[102:105], v[214:217], v[198:201], 0
	v_mfma_f32_16x16x32_bf16 v[98:101], v[222:225], v[198:201], 0
	v_mfma_f32_16x16x32_bf16 v[86:89], v[214:217], v[206:209], 0
	v_mfma_f32_16x16x32_bf16 v[82:85], v[222:225], v[206:209], 0
	v_mfma_f32_16x16x32_bf16 v[134:137], v[218:221], v[172:175], v[134:137]
	v_mfma_f32_16x16x32_bf16 v[130:133], v[242:245], v[172:175], v[130:133]
	v_mfma_f32_16x16x32_bf16 v[118:121], v[218:221], v[194:197], v[118:121]
	v_mfma_f32_16x16x32_bf16 v[114:117], v[242:245], v[194:197], v[114:117]
	v_mfma_f32_16x16x32_bf16 v[102:105], v[218:221], v[202:205], v[102:105]
	v_mfma_f32_16x16x32_bf16 v[98:101], v[242:245], v[202:205], v[98:101]
	v_mfma_f32_16x16x32_bf16 v[86:89], v[218:221], v[210:213], v[86:89]
	v_mfma_f32_16x16x32_bf16 v[82:85], v[242:245], v[210:213], v[82:85]
	s_mov_b32 m0, s30
	v_lshl_add_u64 v[186:187], s[22:23], 0, v[150:151]
	s_barrier
	ds_read_b128 v[168:171], v165 offset:16384
	ds_read_b128 v[172:175], v165 offset:17408
	ds_read_b128 v[190:193], v165 offset:18432
	ds_read_b128 v[194:197], v165 offset:19456
	ds_read_b128 v[198:201], v165 offset:20480
	ds_read_b128 v[202:205], v165 offset:21504
	ds_read_b128 v[206:209], v165 offset:22528
	ds_read_b128 v[210:213], v165 offset:23552
	global_load_lds_dwordx4 v[186:187], off
	s_mov_b32 m0, s31
	v_lshl_add_u64 v[226:227], s[22:23], 0, v[148:149]
	global_load_lds_dwordx4 v[226:227], off
	s_barrier
	s_waitcnt lgkmcnt(0)
	v_mfma_f32_16x16x32_bf16 v[62:65], v[66:69], v[168:171], 0
	v_mfma_f32_16x16x32_bf16 v[58:61], v[74:77], v[168:171], 0
	v_mfma_f32_16x16x32_bf16 v[46:49], v[66:69], v[190:193], 0
	v_mfma_f32_16x16x32_bf16 v[42:45], v[74:77], v[190:193], 0
	v_mfma_f32_16x16x32_bf16 v[30:33], v[66:69], v[198:201], 0
	v_mfma_f32_16x16x32_bf16 v[26:29], v[74:77], v[198:201], 0
	v_mfma_f32_16x16x32_bf16 v[14:17], v[66:69], v[206:209], 0
	v_mfma_f32_16x16x32_bf16 v[10:13], v[74:77], v[206:209], 0
	v_mfma_f32_16x16x32_bf16 v[62:65], v[70:73], v[172:175], v[62:65]
	v_mfma_f32_16x16x32_bf16 v[58:61], v[78:81], v[172:175], v[58:61]
	v_mfma_f32_16x16x32_bf16 v[46:49], v[70:73], v[194:197], v[46:49]
	v_mfma_f32_16x16x32_bf16 v[42:45], v[78:81], v[194:197], v[42:45]
	v_mfma_f32_16x16x32_bf16 v[30:33], v[70:73], v[202:205], v[30:33]
	v_mfma_f32_16x16x32_bf16 v[26:29], v[78:81], v[202:205], v[26:29]
	v_mfma_f32_16x16x32_bf16 v[14:17], v[70:73], v[210:213], v[14:17]
	v_mfma_f32_16x16x32_bf16 v[10:13], v[78:81], v[210:213], v[10:13]
	s_barrier
	s_add_u32 s54, s20, 0x40000
	s_addc_u32 s55, s21, 0
	s_add_i32 s0, s0, s29
	s_mov_b32 m0, s0
	v_lshl_add_u64 v[66:67], s[54:55], 0, v[4:5]
	global_load_lds_dwordx4 v[66:67], off
	s_add_i32 m0, s0, 0x2000
	v_lshl_add_u64 v[66:67], s[54:55], 0, v[146:147]
	global_load_lds_dwordx4 v[66:67], off
	s_waitcnt vmcnt(6)
	s_barrier
; #define PG8_STAGE(bufoff, gbase, voff) do { _Pragma("unroll") for (int _i = 0; _i < 2; ++_i) \
;         __builtin_amdgcn_global_load_lds((const unsigned*)((const char*)(gbase) + (voff)[_i]), (LAS unsigned*)(lds + (bufoff) + ldsw + _i * 8192), 16, 0, 0); } while (0)
; #define PG8_LDA(dst, b, h) do { _Pragma("unroll") for (int m = 0; m < 4; ++m) _Pragma("unroll") for (int k = 0; k < 2; ++k) dst[m][k] = *(const LAS bf16x8*)(lds + PG8_SA(b, h) + aoff + m * 2048 + k * 1024); } while (0)
; #define PG8_LDB(dst, b, h) do { _Pragma("unroll") for (int n = 0; n < 2; ++n) _Pragma("unroll") for (int k = 0; k < 2; ++k) dst[n][k] = *(const LAS bf16x8*)(lds + PG8_SB(b, h) + boff + n * 2048 + k * 1024); } while (0)
; #define PG8_MMA(ai, bj, At, Bt) do { __builtin_amdgcn_s_setprio(1); _Pragma("unroll") for (int m = 0; m < 4; ++m) _Pragma("unroll") for (int n = 0; n < 2; ++n) _Pragma("unroll") for (int k = 0; k < 2; ++k) \
;         acc[ai][bj][m][n] = __builtin_amdgcn_mfma_f32_16x16x32_bf16(Bt[n][k], At[m][k], acc[ai][bj][m][n], 0, 0, 0); __builtin_amdgcn_s_setprio(0); } while (0)
; #define PG8_WAIT_V(n) asm volatile("s_waitcnt vmcnt(" #n ")" ::: "memory")
; #define PG8_WAIT_L(n) asm volatile("s_waitcnt lgkmcnt(" #n ")" ::: "memory")
; #define PG8_BAR __builtin_amdgcn_s_barrier()
; #define PG8_SCHED __builtin_amdgcn_sched_barrier(0)
; template <class Epi>
; __device__ __forceinline__ void gemm_phase(LAS unsigned char* lds, const Gemm g, const StaticOrder& S, const Epi& E) {
;     ...
;             PG8_WAIT_V(6); PG8_BAR; PG8_MMA(1, 1, At, B1); PG8_BAR;
;             PG8_LDB(B0, 1, 0); PG8_SCHED; PG8_LDA(At, 1, 0); PG8_STAGE(PG8_SA(0, 1), a2 + hstep, voffA);
;             PG8_WAIT_L(8); PG8_BAR; PG8_WAIT_L(0); PG8_MMA(0, 0, At, B0); PG8_BAR; PG8_SCHED;
;             PG8_LDB(B1, 1, 1); PG8_STAGE(PG8_SB(1, 0), b3, voffB);
;             PG8_BAR; PG8_WAIT_L(0); PG8_MMA(0, 1, At, B1); PG8_BAR;
	v_mfma_f32_16x16x32_bf16 v[54:57], v[214:217], v[168:171], 0
	v_mfma_f32_16x16x32_bf16 v[50:53], v[222:225], v[168:171], 0
	v_mfma_f32_16x16x32_bf16 v[38:41], v[214:217], v[190:193], 0
	v_mfma_f32_16x16x32_bf16 v[34:37], v[222:225], v[190:193], 0
	v_mfma_f32_16x16x32_bf16 v[22:25], v[214:217], v[198:201], 0
	v_mfma_f32_16x16x32_bf16 v[18:21], v[222:225], v[198:201], 0
	v_mfma_f32_16x16x32_bf16 v[6:9], v[214:217], v[206:209], 0
	v_mfma_f32_16x16x32_bf16 v[0:3], v[222:225], v[206:209], 0
	v_mfma_f32_16x16x32_bf16 v[54:57], v[218:221], v[172:175], v[54:57]
	v_mfma_f32_16x16x32_bf16 v[50:53], v[242:245], v[172:175], v[50:53]
	v_mfma_f32_16x16x32_bf16 v[38:41], v[218:221], v[194:197], v[38:41]
	v_mfma_f32_16x16x32_bf16 v[34:37], v[242:245], v[194:197], v[34:37]
	v_mfma_f32_16x16x32_bf16 v[22:25], v[218:221], v[202:205], v[22:25]
	v_mfma_f32_16x16x32_bf16 v[18:21], v[242:245], v[202:205], v[18:21]
	v_mfma_f32_16x16x32_bf16 v[6:9], v[218:221], v[210:213], v[6:9]
	v_mfma_f32_16x16x32_bf16 v[0:3], v[242:245], v[210:213], v[0:3]
	s_add_i32 s0, 0, 0x18000
	v_add_u32_e32 v78, s0, v161
	s_barrier
	ds_read_b128 v[66:69], v78
	ds_read_b128 v[70:73], v78 offset:1024
	ds_read_b128 v[74:77], v78 offset:2048
	ds_read_b128 v[78:81], v78 offset:3072
	s_add_u32 s22, s22, 0x40000
	s_addc_u32 s23, s23, 0
	s_mov_b32 m0, s34
	v_lshl_add_u64 v[214:215], s[22:23], 0, v[150:151]
	ds_read_b128 v[168:171], v165 offset:32768
	ds_read_b128 v[172:175], v165 offset:33792
	ds_read_b128 v[190:193], v165 offset:34816
	ds_read_b128 v[194:197], v165 offset:35840
	ds_read_b128 v[198:201], v165 offset:36864
	ds_read_b128 v[202:205], v165 offset:37888
	ds_read_b128 v[206:209], v165 offset:38912
	ds_read_b128 v[210:213], v165 offset:39936
	global_load_lds_dwordx4 v[214:215], off
	s_mov_b32 m0, s35
	v_lshl_add_u64 v[214:215], s[22:23], 0, v[148:149]
	global_load_lds_dwordx4 v[214:215], off
	s_waitcnt lgkmcnt(8)
	s_barrier
	s_waitcnt lgkmcnt(0)
	v_mfma_f32_16x16x32_bf16 v[142:145], v[66:69], v[168:171], v[142:145]
	v_mfma_f32_16x16x32_bf16 v[138:141], v[74:77], v[168:171], v[138:141]
	v_mfma_f32_16x16x32_bf16 v[126:129], v[66:69], v[190:193], v[126:129]
	v_mfma_f32_16x16x32_bf16 v[122:125], v[74:77], v[190:193], v[122:125]
	v_mfma_f32_16x16x32_bf16 v[110:113], v[66:69], v[198:201], v[110:113]
	v_mfma_f32_16x16x32_bf16 v[106:109], v[74:77], v[198:201], v[106:109]
	v_mfma_f32_16x16x32_bf16 v[94:97], v[66:69], v[206:209], v[94:97]
	v_mfma_f32_16x16x32_bf16 v[90:93], v[74:77], v[206:209], v[90:93]
	v_mfma_f32_16x16x32_bf16 v[142:145], v[70:73], v[172:175], v[142:145]
	v_mfma_f32_16x16x32_bf16 v[138:141], v[78:81], v[172:175], v[138:141]
	v_mfma_f32_16x16x32_bf16 v[126:129], v[70:73], v[194:197], v[126:129]
	v_mfma_f32_16x16x32_bf16 v[122:125], v[78:81], v[194:197], v[122:125]
	v_mfma_f32_16x16x32_bf16 v[110:113], v[70:73], v[202:205], v[110:113]
	v_mfma_f32_16x16x32_bf16 v[106:109], v[78:81], v[202:205], v[106:109]
	v_mfma_f32_16x16x32_bf16 v[94:97], v[70:73], v[210:213], v[94:97]
	v_mfma_f32_16x16x32_bf16 v[90:93], v[78:81], v[210:213], v[90:93]
	s_barrier
	s_add_i32 s1, 0, 0x1c000
	s_add_i32 s0, s0, s29
	v_add_u32_e32 v158, s1, v161
	v_lshl_add_u64 v[156:157], v[156:157], 0, s[86:87]
	s_mov_b32 m0, s0
	ds_read_b128 v[214:217], v158
	ds_read_b128 v[218:221], v158 offset:1024
	ds_read_b128 v[222:225], v158 offset:2048
	ds_read_b128 v[242:245], v158 offset:3072
	global_load_lds_dwordx4 v[156:157], off
	s_add_i32 m0, s0, 0x2000
	v_lshl_add_u64 v[156:157], v[176:177], 0, s[86:87]
	global_load_lds_dwordx4 v[156:157], off
	s_barrier
; #define PG8_STAGE(bufoff, gbase, voff) do { _Pragma("unroll") for (int _i = 0; _i < 2; ++_i) \
;         __builtin_amdgcn_global_load_lds((const unsigned*)((const char*)(gbase) + (voff)[_i]), (LAS unsigned*)(lds + (bufoff) + ldsw + _i * 8192), 16, 0, 0); } while (0)
; #define PG8_LDA(dst, b, h) do { _Pragma("unroll") for (int m = 0; m < 4; ++m) _Pragma("unroll") for (int k = 0; k < 2; ++k) dst[m][k] = *(const LAS bf16x8*)(lds + PG8_SA(b, h) + aoff + m * 2048 + k * 1024); } while (0)
; #define PG8_LDB(dst, b, h) do { _Pragma("unroll") for (int n = 0; n < 2; ++n) _Pragma("unroll") for (int k = 0; k < 2; ++k) dst[n][k] = *(const LAS bf16x8*)(lds + PG8_SB(b, h) + boff + n * 2048 + k * 1024); } while (0)
; #define PG8_MMA(ai, bj, At, Bt) do { __builtin_amdgcn_s_setprio(1); _Pragma("unroll") for (int m = 0; m < 4; ++m) _Pragma("unroll") for (int n = 0; n < 2; ++n) _Pragma("unroll") for (int k = 0; k < 2; ++k) \
;         acc[ai][bj][m][n] = __builtin_amdgcn_mfma_f32_16x16x32_bf16(Bt[n][k], At[m][k], acc[ai][bj][m][n], 0, 0, 0); __builtin_amdgcn_s_setprio(0); } while (0)
; #define PG8_WAIT_V(n) asm volatile("s_waitcnt vmcnt(" #n ")" ::: "memory")
; #define PG8_WAIT_L(n) asm volatile("s_waitcnt lgkmcnt(" #n ")" ::: "memory")
; #define PG8_BAR __builtin_amdgcn_s_barrier()
; #define PG8_SCHED __builtin_amdgcn_sched_barrier(0)
; template <class Epi>
; __device__ __forceinline__ void gemm_phase(LAS unsigned char* lds, const Gemm g, const StaticOrder& S, const Epi& E) {
;     ...
;             PG8_LDB(B1, 1, 1); PG8_STAGE(PG8_SB(1, 0), b3, voffB);
;             PG8_BAR; PG8_WAIT_L(0); PG8_MMA(0, 1, At, B1); PG8_BAR;
;             PG8_LDA(At, 1, 1); PG8_STAGE(PG8_SA(1, 0), a3, voffA);
;             PG8_BAR; PG8_WAIT_L(0); PG8_MMA(1, 0, At, B0); PG8_BAR; PG8_SCHED;
;             PG8_STAGE(PG8_SB(1, 1), b3 + hstep, voffB);
;             PG8_WAIT_V(6); PG8_BAR; PG8_MMA(1, 1, At, B1); PG8_BAR;
	s_waitcnt lgkmcnt(0)
	v_mfma_f32_16x16x32_bf16 v[134:137], v[214:217], v[168:171], v[134:137]
	v_mfma_f32_16x16x32_bf16 v[130:133], v[222:225], v[168:171], v[130:133]
	v_mfma_f32_16x16x32_bf16 v[118:121], v[214:217], v[190:193], v[118:121]
	v_mfma_f32_16x16x32_bf16 v[114:117], v[222:225], v[190:193], v[114:117]
	v_mfma_f32_16x16x32_bf16 v[102:105], v[214:217], v[198:201], v[102:105]
	v_mfma_f32_16x16x32_bf16 v[98:101], v[222:225], v[198:201], v[98:101]
	v_mfma_f32_16x16x32_bf16 v[86:89], v[214:217], v[206:209], v[86:89]
	v_mfma_f32_16x16x32_bf16 v[82:85], v[222:225], v[206:209], v[82:85]
	v_mfma_f32_16x16x32_bf16 v[134:137], v[218:221], v[172:175], v[134:137]
	v_mfma_f32_16x16x32_bf16 v[130:133], v[242:245], v[172:175], v[130:133]
	v_mfma_f32_16x16x32_bf16 v[118:121], v[218:221], v[194:197], v[118:121]
	v_mfma_f32_16x16x32_bf16 v[114:117], v[242:245], v[194:197], v[114:117]
	v_mfma_f32_16x16x32_bf16 v[102:105], v[218:221], v[202:205], v[102:105]
	v_mfma_f32_16x16x32_bf16 v[98:101], v[242:245], v[202:205], v[98:101]
	v_mfma_f32_16x16x32_bf16 v[86:89], v[218:221], v[210:213], v[86:89]
	v_mfma_f32_16x16x32_bf16 v[82:85], v[242:245], v[210:213], v[82:85]
	s_mov_b32 m0, s38
	v_lshl_add_u64 v[156:157], v[186:187], 0, s[86:87]
	s_barrier
	ds_read_b128 v[168:171], v165 offset:49152
	ds_read_b128 v[172:175], v165 offset:50176
	ds_read_b128 v[190:193], v165 offset:51200
	ds_read_b128 v[194:197], v165 offset:52224
	ds_read_b128 v[198:201], v165 offset:53248
	ds_read_b128 v[202:205], v165 offset:54272
	ds_read_b128 v[206:209], v165 offset:55296
	ds_read_b128 v[210:213], v165 offset:56320
	global_load_lds_dwordx4 v[156:157], off
	s_mov_b32 m0, s39
	v_lshl_add_u64 v[156:157], v[226:227], 0, s[86:87]
	global_load_lds_dwordx4 v[156:157], off
	s_barrier
	s_waitcnt lgkmcnt(0)
	v_mfma_f32_16x16x32_bf16 v[62:65], v[66:69], v[168:171], v[62:65]
	v_mfma_f32_16x16x32_bf16 v[58:61], v[74:77], v[168:171], v[58:61]
	v_mfma_f32_16x16x32_bf16 v[46:49], v[66:69], v[190:193], v[46:49]
	v_mfma_f32_16x16x32_bf16 v[42:45], v[74:77], v[190:193], v[42:45]
	v_mfma_f32_16x16x32_bf16 v[30:33], v[66:69], v[198:201], v[30:33]
	v_mfma_f32_16x16x32_bf16 v[26:29], v[74:77], v[198:201], v[26:29]
	v_mfma_f32_16x16x32_bf16 v[14:17], v[66:69], v[206:209], v[14:17]
	v_mfma_f32_16x16x32_bf16 v[10:13], v[74:77], v[206:209], v[10:13]
	v_mfma_f32_16x16x32_bf16 v[62:65], v[70:73], v[172:175], v[62:65]
	v_mfma_f32_16x16x32_bf16 v[58:61], v[78:81], v[172:175], v[58:61]
	v_mfma_f32_16x16x32_bf16 v[46:49], v[70:73], v[194:197], v[46:49]
	v_mfma_f32_16x16x32_bf16 v[42:45], v[78:81], v[194:197], v[42:45]
	v_mfma_f32_16x16x32_bf16 v[30:33], v[70:73], v[202:205], v[30:33]
	v_mfma_f32_16x16x32_bf16 v[26:29], v[78:81], v[202:205], v[26:29]
	v_mfma_f32_16x16x32_bf16 v[14:17], v[70:73], v[210:213], v[14:17]
	v_mfma_f32_16x16x32_bf16 v[10:13], v[78:81], v[210:213], v[10:13]
	s_barrier
	s_add_u32 s20, s20, 0x40080
	s_addc_u32 s21, s21, 0
	s_add_i32 s0, s1, s29
	s_mov_b32 m0, s0
	v_lshl_add_u64 v[66:67], s[20:21], 0, v[4:5]
	global_load_lds_dwordx4 v[66:67], off
	s_add_i32 m0, s0, 0x2000
	v_lshl_add_u64 v[66:67], s[20:21], 0, v[146:147]
	global_load_lds_dwordx4 v[66:67], off
	s_waitcnt vmcnt(6)
	s_barrier
	v_mfma_f32_16x16x32_bf16 v[54:57], v[214:217], v[168:171], v[54:57]
	v_mfma_f32_16x16x32_bf16 v[50:53], v[222:225], v[168:171], v[50:53]
	v_mfma_f32_16x16x32_bf16 v[38:41], v[214:217], v[190:193], v[38:41]
	v_mfma_f32_16x16x32_bf16 v[34:37], v[222:225], v[190:193], v[34:37]
	v_mfma_f32_16x16x32_bf16 v[22:25], v[214:217], v[198:201], v[22:25]
	v_mfma_f32_16x16x32_bf16 v[18:21], v[222:225], v[198:201], v[18:21]
	v_mfma_f32_16x16x32_bf16 v[6:9], v[214:217], v[206:209], v[6:9]
	v_mfma_f32_16x16x32_bf16 v[0:3], v[222:225], v[206:209], v[0:3]
	v_mfma_f32_16x16x32_bf16 v[54:57], v[218:221], v[172:175], v[54:57]
	v_mfma_f32_16x16x32_bf16 v[50:53], v[242:245], v[172:175], v[50:53]
	v_mfma_f32_16x16x32_bf16 v[38:41], v[218:221], v[194:197], v[38:41]
	v_mfma_f32_16x16x32_bf16 v[34:37], v[242:245], v[194:197], v[34:37]
	v_mfma_f32_16x16x32_bf16 v[22:25], v[218:221], v[202:205], v[22:25]
	v_mfma_f32_16x16x32_bf16 v[18:21], v[242:245], v[202:205], v[18:21]
	v_mfma_f32_16x16x32_bf16 v[6:9], v[218:221], v[210:213], v[6:9]
	v_mfma_f32_16x16x32_bf16 v[0:3], v[242:245], v[210:213], v[0:3]
	s_add_i32 s52, s52, 2
	s_add_u32 s18, s18, 0x100
	s_addc_u32 s19, s19, 0
	s_add_u32 s50, s50, 0x100
	s_addc_u32 s51, s51, 0
	s_cmp_gt_u32 s52, 13
	s_barrier
	s_cbranch_scc1 .Lpeel_exit_1
	.p2align 6

; #define PG8_STAGE(bufoff, gbase, voff) do { _Pragma("unroll") for (int _i = 0; _i < 2; ++_i) \
;         __builtin_amdgcn_global_load_lds((const unsigned*)((const char*)(gbase) + (voff)[_i]), (LAS unsigned*)(lds + (bufoff) + ldsw + _i * 8192), 16, 0, 0); } while (0)
; #define PG8_LDA(dst, b, h) do { _Pragma("unroll") for (int m = 0; m < 4; ++m) _Pragma("unroll") for (int k = 0; k < 2; ++k) dst[m][k] = *(const LAS bf16x8*)(lds + PG8_SA(b, h) + aoff + m * 2048 + k * 1024); } while (0)
; #define PG8_LDB(dst, b, h) do { _Pragma("unroll") for (int n = 0; n < 2; ++n) _Pragma("unroll") for (int k = 0; k < 2; ++k) dst[n][k] = *(const LAS bf16x8*)(lds + PG8_SB(b, h) + boff + n * 2048 + k * 1024); } while (0)
; #define PG8_MMA(ai, bj, At, Bt) do { __builtin_amdgcn_s_setprio(1); _Pragma("unroll") for (int m = 0; m < 4; ++m) _Pragma("unroll") for (int n = 0; n < 2; ++n) _Pragma("unroll") for (int k = 0; k < 2; ++k) \
;         acc[ai][bj][m][n] = __builtin_amdgcn_mfma_f32_16x16x32_bf16(Bt[n][k], At[m][k], acc[ai][bj][m][n], 0, 0, 0); __builtin_amdgcn_s_setprio(0); } while (0)
; #define PG8_WAIT_L(n) asm volatile("s_waitcnt lgkmcnt(" #n ")" ::: "memory")
; #define PG8_BAR __builtin_amdgcn_s_barrier()
; #define PG8_SCHED __builtin_amdgcn_sched_barrier(0)
; template <class Epi>
; __device__ __forceinline__ void gemm_phase(LAS unsigned char* lds, const Gemm g, const StaticOrder& S, const Epi& E) {
;     ...
;         for (int t = 0; t < nt; t += 2) {
;             const bool last = (t == nt - 2);
;             const char* a1 = cA + (size_t)(t + 1) * kstep;
;             const char* a2 = last ? nA : cA + (size_t)(t + 2) * kstep; const char* b2 = last ? nB : cB + (size_t)(t + 2) * kstep;
;             const char* a3 = a2 + kstep; const char* b3 = b2 + kstep;
;             PG8_LDB(B0, 0, 0); PG8_SCHED; PG8_LDA(At, 0, 0); PG8_STAGE(PG8_SA(1, 1), a1 + hstep, voffA);
;             PG8_WAIT_L(8); PG8_BAR; PG8_WAIT_L(0); PG8_MMA(0, 0, At, B0); PG8_BAR; PG8_SCHED;
;             PG8_LDB(B1, 0, 1); PG8_STAGE(PG8_SB(0, 0), b2, voffB);
;             PG8_BAR; PG8_WAIT_L(0); PG8_MMA(0, 1, At, B1); PG8_BAR;
;             PG8_LDA(At, 0, 1); PG8_STAGE(PG8_SA(0, 0), a2, voffA);
;             PG8_BAR; PG8_WAIT_L(0); PG8_MMA(1, 0, At, B0); PG8_BAR; PG8_SCHED;
;             PG8_STAGE(PG8_SB(0, 1), b2 + hstep, voffB);
.Lsp_skip_0:
	s_add_i32 s64, s26, 2
	s_add_u32 s0, s8, 0x80
	s_addc_u32 s1, s9, 0
	s_add_i32 s65, 0, 0x10000
	v_add_u32_e32 v4, s65, v245
	ds_read_b128 v[132:135], v4
	ds_read_b128 v[136:139], v4 offset:1024
	ds_read_b128 v[140:143], v4 offset:2048
	ds_read_b128 v[144:147], v4 offset:3072
	s_cmp_eq_u32 s57, s26
	s_cselect_b32 s26, s24, s0
	s_cselect_b32 s27, s25, s1
	s_cselect_b32 s29, s11, s63
	s_cselect_b32 s28, s10, s62
	v_lshl_add_u64 v[6:7], s[8:9], 0, v[164:165]
	s_add_i32 m0, s39, 0xc000
	ds_read_b128 v[148:151], v249
	ds_read_b128 v[152:155], v249 offset:1024
	ds_read_b128 v[156:159], v249 offset:2048
	ds_read_b128 v[168:171], v249 offset:3072
	ds_read_b128 v[172:175], v249 offset:4096
	ds_read_b128 v[190:193], v249 offset:5120
	ds_read_b128 v[194:197], v249 offset:6144
	ds_read_b128 v[198:201], v249 offset:7168
	global_load_lds_dwordx4 v[6:7], off
	s_add_i32 m0, s39, 0xe000
	v_lshl_add_u64 v[6:7], s[8:9], 0, v[166:167]
	global_load_lds_dwordx4 v[6:7], off
	s_waitcnt lgkmcnt(8)
	s_barrier
	s_waitcnt lgkmcnt(0)
	v_mfma_f32_16x16x32_bf16 v[80:83], v[132:135], v[148:151], 0
	v_mfma_f32_16x16x32_bf16 v[104:107], v[140:143], v[148:151], 0
	v_mfma_f32_16x16x32_bf16 v[128:131], v[132:135], v[156:159], 0
	v_mfma_f32_16x16x32_bf16 v[100:103], v[140:143], v[156:159], 0
	v_mfma_f32_16x16x32_bf16 v[124:127], v[132:135], v[172:175], 0
	v_mfma_f32_16x16x32_bf16 v[96:99], v[140:143], v[172:175], 0
	v_mfma_f32_16x16x32_bf16 v[120:123], v[132:135], v[194:197], 0
	v_mfma_f32_16x16x32_bf16 v[88:91], v[140:143], v[194:197], 0
	v_mfma_f32_16x16x32_bf16 v[80:83], v[136:139], v[152:155], v[80:83]
	v_mfma_f32_16x16x32_bf16 v[104:107], v[144:147], v[152:155], v[104:107]
	v_mfma_f32_16x16x32_bf16 v[128:131], v[136:139], v[168:171], v[128:131]
	v_mfma_f32_16x16x32_bf16 v[100:103], v[144:147], v[168:171], v[100:103]
	v_mfma_f32_16x16x32_bf16 v[124:127], v[136:139], v[190:193], v[124:127]
	v_mfma_f32_16x16x32_bf16 v[96:99], v[144:147], v[190:193], v[96:99]
	v_mfma_f32_16x16x32_bf16 v[120:123], v[136:139], v[198:201], v[120:123]
	v_mfma_f32_16x16x32_bf16 v[88:91], v[144:147], v[198:201], v[88:91]
	s_barrier
	s_add_i32 s70, 0, 0x14000
	s_add_i32 s0, s65, s34
	v_add_u32_e32 v4, s70, v245
	v_lshl_add_u64 v[176:177], s[28:29], 0, v[162:163]
	s_mov_b32 m0, s0
	ds_read_b128 v[202:205], v4
	ds_read_b128 v[206:209], v4 offset:1024
	ds_read_b128 v[210:213], v4 offset:2048
	ds_read_b128 v[214:217], v4 offset:3072
	global_load_lds_dwordx4 v[176:177], off
	s_add_i32 m0, s0, 0x2000
	v_lshl_add_u64 v[186:187], s[28:29], 0, v[160:161]
	global_load_lds_dwordx4 v[186:187], off
	s_barrier
	s_waitcnt lgkmcnt(0)
	v_mfma_f32_16x16x32_bf16 v[64:67], v[202:205], v[148:151], 0
	v_mfma_f32_16x16x32_bf16 v[32:35], v[210:213], v[148:151], 0
	v_mfma_f32_16x16x32_bf16 v[60:63], v[202:205], v[156:159], 0
	v_mfma_f32_16x16x32_bf16 v[28:31], v[210:213], v[156:159], 0
	v_mfma_f32_16x16x32_bf16 v[56:59], v[202:205], v[172:175], 0
	v_mfma_f32_16x16x32_bf16 v[24:27], v[210:213], v[172:175], 0
	v_mfma_f32_16x16x32_bf16 v[52:55], v[202:205], v[194:197], 0
	v_mfma_f32_16x16x32_bf16 v[20:23], v[210:213], v[194:197], 0
	v_mfma_f32_16x16x32_bf16 v[64:67], v[206:209], v[152:155], v[64:67]
	v_mfma_f32_16x16x32_bf16 v[32:35], v[214:217], v[152:155], v[32:35]
	v_mfma_f32_16x16x32_bf16 v[60:63], v[206:209], v[168:171], v[60:63]
	v_mfma_f32_16x16x32_bf16 v[28:31], v[214:217], v[168:171], v[28:31]
	v_mfma_f32_16x16x32_bf16 v[56:59], v[206:209], v[190:193], v[56:59]
	v_mfma_f32_16x16x32_bf16 v[24:27], v[214:217], v[190:193], v[24:27]
	v_mfma_f32_16x16x32_bf16 v[52:55], v[206:209], v[198:201], v[52:55]
	v_mfma_f32_16x16x32_bf16 v[20:23], v[214:217], v[198:201], v[20:23]
	s_mov_b32 m0, s39
	v_lshl_add_u64 v[218:219], s[26:27], 0, v[162:163]
	s_barrier
	ds_read_b128 v[148:151], v249 offset:16384
	ds_read_b128 v[152:155], v249 offset:17408
	ds_read_b128 v[156:159], v249 offset:18432
	ds_read_b128 v[168:171], v249 offset:19456
	ds_read_b128 v[172:175], v249 offset:20480
	ds_read_b128 v[190:193], v249 offset:21504
	ds_read_b128 v[194:197], v249 offset:22528
	ds_read_b128 v[198:201], v249 offset:23552
	global_load_lds_dwordx4 v[218:219], off
	s_mov_b32 m0, s40
	v_lshl_add_u64 v[220:221], s[26:27], 0, v[160:161]
	global_load_lds_dwordx4 v[220:221], off
	s_barrier
	s_waitcnt lgkmcnt(0)
	v_mfma_f32_16x16x32_bf16 v[92:95], v[132:135], v[148:151], 0
	v_mfma_f32_16x16x32_bf16 v[84:87], v[140:143], v[148:151], 0
	v_mfma_f32_16x16x32_bf16 v[116:119], v[132:135], v[156:159], 0
	v_mfma_f32_16x16x32_bf16 v[76:79], v[140:143], v[156:159], 0
	v_mfma_f32_16x16x32_bf16 v[112:115], v[132:135], v[172:175], 0
	v_mfma_f32_16x16x32_bf16 v[72:75], v[140:143], v[172:175], 0
	v_mfma_f32_16x16x32_bf16 v[108:111], v[132:135], v[194:197], 0
	v_mfma_f32_16x16x32_bf16 v[68:71], v[140:143], v[194:197], 0
	v_mfma_f32_16x16x32_bf16 v[92:95], v[136:139], v[152:155], v[92:95]
	v_mfma_f32_16x16x32_bf16 v[84:87], v[144:147], v[152:155], v[84:87]
	v_mfma_f32_16x16x32_bf16 v[116:119], v[136:139], v[168:171], v[116:119]
	v_mfma_f32_16x16x32_bf16 v[76:79], v[144:147], v[168:171], v[76:79]
	v_mfma_f32_16x16x32_bf16 v[112:115], v[136:139], v[190:193], v[112:115]
	v_mfma_f32_16x16x32_bf16 v[72:75], v[144:147], v[190:193], v[72:75]
	v_mfma_f32_16x16x32_bf16 v[108:111], v[136:139], v[198:201], v[108:111]
	v_mfma_f32_16x16x32_bf16 v[68:71], v[144:147], v[198:201], v[68:71]
	s_barrier
	s_add_u32 s0, s28, s52
	s_addc_u32 s1, s29, 0
	s_add_i32 s28, s70, s34
	v_lshl_add_u64 v[222:223], s[0:1], 0, v[162:163]
	s_mov_b32 m0, s28
	v_lshl_add_u64 v[224:225], s[0:1], 0, v[160:161]
	global_load_lds_dwordx4 v[222:223], off
	s_add_i32 m0, s28, 0x2000
	s_nop 0
	global_load_lds_dwordx4 v[224:225], off
	s_waitcnt vmcnt(6)
	s_barrier
; #define PG8_STAGE(bufoff, gbase, voff) do { _Pragma("unroll") for (int _i = 0; _i < 2; ++_i) \
;         __builtin_amdgcn_global_load_lds((const unsigned*)((const char*)(gbase) + (voff)[_i]), (LAS unsigned*)(lds + (bufoff) + ldsw + _i * 8192), 16, 0, 0); } while (0)
; #define PG8_LDA(dst, b, h) do { _Pragma("unroll") for (int m = 0; m < 4; ++m) _Pragma("unroll") for (int k = 0; k < 2; ++k) dst[m][k] = *(const LAS bf16x8*)(lds + PG8_SA(b, h) + aoff + m * 2048 + k * 1024); } while (0)
; #define PG8_LDB(dst, b, h) do { _Pragma("unroll") for (int n = 0; n < 2; ++n) _Pragma("unroll") for (int k = 0; k < 2; ++k) dst[n][k] = *(const LAS bf16x8*)(lds + PG8_SB(b, h) + boff + n * 2048 + k * 1024); } while (0)
; #define PG8_MMA(ai, bj, At, Bt) do { __builtin_amdgcn_s_setprio(1); _Pragma("unroll") for (int m = 0; m < 4; ++m) _Pragma("unroll") for (int n = 0; n < 2; ++n) _Pragma("unroll") for (int k = 0; k < 2; ++k) \
;         acc[ai][bj][m][n] = __builtin_amdgcn_mfma_f32_16x16x32_bf16(Bt[n][k], At[m][k], acc[ai][bj][m][n], 0, 0, 0); __builtin_amdgcn_s_setprio(0); } while (0)
; #define PG8_WAIT_V(n) asm volatile("s_waitcnt vmcnt(" #n ")" ::: "memory")
; #define PG8_WAIT_L(n) asm volatile("s_waitcnt lgkmcnt(" #n ")" ::: "memory")
; #define PG8_BAR __builtin_amdgcn_s_barrier()
; #define PG8_SCHED __builtin_amdgcn_sched_barrier(0)
; template <class Epi>
; __device__ __forceinline__ void gemm_phase(LAS unsigned char* lds, const Gemm g, const StaticOrder& S, const Epi& E) {
;     ...
;             PG8_WAIT_V(6); PG8_BAR; PG8_MMA(1, 1, At, B1); PG8_BAR;
;             PG8_LDB(B0, 1, 0); PG8_SCHED; PG8_LDA(At, 1, 0); PG8_STAGE(PG8_SA(0, 1), a2 + hstep, voffA);
;             PG8_WAIT_L(8); PG8_BAR; PG8_WAIT_L(0); PG8_MMA(0, 0, At, B0); PG8_BAR; PG8_SCHED;
;             PG8_LDB(B1, 1, 1); PG8_STAGE(PG8_SB(1, 0), b3, voffB);
;             PG8_BAR; PG8_WAIT_L(0); PG8_MMA(0, 1, At, B1); PG8_BAR;
;             PG8_LDA(At, 1, 1); PG8_STAGE(PG8_SA(1, 0), a3, voffA);
	v_mfma_f32_16x16x32_bf16 v[48:51], v[202:205], v[148:151], 0
	v_mfma_f32_16x16x32_bf16 v[16:19], v[210:213], v[148:151], 0
	v_mfma_f32_16x16x32_bf16 v[44:47], v[202:205], v[156:159], 0
	v_mfma_f32_16x16x32_bf16 v[12:15], v[210:213], v[156:159], 0
	v_mfma_f32_16x16x32_bf16 v[40:43], v[202:205], v[172:175], 0
	v_mfma_f32_16x16x32_bf16 v[6:9], v[210:213], v[172:175], 0
	v_mfma_f32_16x16x32_bf16 v[36:39], v[202:205], v[194:197], 0
	v_mfma_f32_16x16x32_bf16 v[0:3], v[210:213], v[194:197], 0
	v_mfma_f32_16x16x32_bf16 v[48:51], v[206:209], v[152:155], v[48:51]
	v_mfma_f32_16x16x32_bf16 v[16:19], v[214:217], v[152:155], v[16:19]
	v_mfma_f32_16x16x32_bf16 v[44:47], v[206:209], v[168:171], v[44:47]
	v_mfma_f32_16x16x32_bf16 v[12:15], v[214:217], v[168:171], v[12:15]
	v_mfma_f32_16x16x32_bf16 v[40:43], v[206:209], v[190:193], v[40:43]
	v_mfma_f32_16x16x32_bf16 v[6:9], v[214:217], v[190:193], v[6:9]
	v_mfma_f32_16x16x32_bf16 v[36:39], v[206:209], v[198:201], v[36:39]
	v_mfma_f32_16x16x32_bf16 v[0:3], v[214:217], v[198:201], v[0:3]
	s_add_i32 s28, 0, 0x18000
	v_add_u32_e32 v4, s28, v245
	s_barrier
	ds_read_b128 v[132:135], v4
	ds_read_b128 v[136:139], v4 offset:1024
	ds_read_b128 v[140:143], v4 offset:2048
	ds_read_b128 v[144:147], v4 offset:3072
	s_add_u32 s0, s26, s52
	s_addc_u32 s1, s27, 0
	s_mov_b32 m0, s41
	v_lshl_add_u64 v[10:11], s[0:1], 0, v[162:163]
	ds_read_b128 v[148:151], v249 offset:32768
	ds_read_b128 v[152:155], v249 offset:33792
	ds_read_b128 v[156:159], v249 offset:34816
	ds_read_b128 v[168:171], v249 offset:35840
	ds_read_b128 v[172:175], v249 offset:36864
	ds_read_b128 v[190:193], v249 offset:37888
	ds_read_b128 v[194:197], v249 offset:38912
	ds_read_b128 v[198:201], v249 offset:39936
	global_load_lds_dwordx4 v[10:11], off
	s_mov_b32 m0, s42
	v_lshl_add_u64 v[10:11], s[0:1], 0, v[160:161]
	global_load_lds_dwordx4 v[10:11], off
	s_waitcnt lgkmcnt(8)
	s_barrier
	s_waitcnt lgkmcnt(0)
	v_mfma_f32_16x16x32_bf16 v[80:83], v[132:135], v[148:151], v[80:83]
	v_mfma_f32_16x16x32_bf16 v[104:107], v[140:143], v[148:151], v[104:107]
	v_mfma_f32_16x16x32_bf16 v[128:131], v[132:135], v[156:159], v[128:131]
	v_mfma_f32_16x16x32_bf16 v[100:103], v[140:143], v[156:159], v[100:103]
	v_mfma_f32_16x16x32_bf16 v[124:127], v[132:135], v[172:175], v[124:127]
	v_mfma_f32_16x16x32_bf16 v[96:99], v[140:143], v[172:175], v[96:99]
	v_mfma_f32_16x16x32_bf16 v[120:123], v[132:135], v[194:197], v[120:123]
	v_mfma_f32_16x16x32_bf16 v[88:91], v[140:143], v[194:197], v[88:91]
	v_mfma_f32_16x16x32_bf16 v[80:83], v[136:139], v[152:155], v[80:83]
	v_mfma_f32_16x16x32_bf16 v[104:107], v[144:147], v[152:155], v[104:107]
	v_mfma_f32_16x16x32_bf16 v[128:131], v[136:139], v[168:171], v[128:131]
	v_mfma_f32_16x16x32_bf16 v[100:103], v[144:147], v[168:171], v[100:103]
	v_mfma_f32_16x16x32_bf16 v[124:127], v[136:139], v[190:193], v[124:127]
	v_mfma_f32_16x16x32_bf16 v[96:99], v[144:147], v[190:193], v[96:99]
	v_mfma_f32_16x16x32_bf16 v[120:123], v[136:139], v[198:201], v[120:123]
	v_mfma_f32_16x16x32_bf16 v[88:91], v[144:147], v[198:201], v[88:91]
	s_barrier
	s_add_i32 s0, 0, 0x1c000
	s_add_i32 s1, s28, s34
	v_add_u32_e32 v4, s0, v245
	v_lshl_add_u64 v[10:11], v[176:177], 0, s[86:87]
	s_mov_b32 m0, s1
	ds_read_b128 v[202:205], v4
	ds_read_b128 v[206:209], v4 offset:1024
	ds_read_b128 v[210:213], v4 offset:2048
	ds_read_b128 v[214:217], v4 offset:3072
	global_load_lds_dwordx4 v[10:11], off
	s_add_i32 m0, s1, 0x2000
	v_lshl_add_u64 v[10:11], v[186:187], 0, s[86:87]
	global_load_lds_dwordx4 v[10:11], off
	s_barrier
; #define PG8_STAGE(bufoff, gbase, voff) do { _Pragma("unroll") for (int _i = 0; _i < 2; ++_i) \
;         __builtin_amdgcn_global_load_lds((const unsigned*)((const char*)(gbase) + (voff)[_i]), (LAS unsigned*)(lds + (bufoff) + ldsw + _i * 8192), 16, 0, 0); } while (0)
; #define PG8_LDA(dst, b, h) do { _Pragma("unroll") for (int m = 0; m < 4; ++m) _Pragma("unroll") for (int k = 0; k < 2; ++k) dst[m][k] = *(const LAS bf16x8*)(lds + PG8_SA(b, h) + aoff + m * 2048 + k * 1024); } while (0)
; #define PG8_MMA(ai, bj, At, Bt) do { __builtin_amdgcn_s_setprio(1); _Pragma("unroll") for (int m = 0; m < 4; ++m) _Pragma("unroll") for (int n = 0; n < 2; ++n) _Pragma("unroll") for (int k = 0; k < 2; ++k) \
;         acc[ai][bj][m][n] = __builtin_amdgcn_mfma_f32_16x16x32_bf16(Bt[n][k], At[m][k], acc[ai][bj][m][n], 0, 0, 0); __builtin_amdgcn_s_setprio(0); } while (0)
; #define PG8_WAIT_V(n) asm volatile("s_waitcnt vmcnt(" #n ")" ::: "memory")
; #define PG8_WAIT_L(n) asm volatile("s_waitcnt lgkmcnt(" #n ")" ::: "memory")
; #define PG8_BAR __builtin_amdgcn_s_barrier()
; #define PG8_SCHED __builtin_amdgcn_sched_barrier(0)
; template <class Epi>
; __device__ __forceinline__ void gemm_phase(LAS unsigned char* lds, const Gemm g, const StaticOrder& S, const Epi& E) {
;     ...
;             PG8_LDA(At, 1, 1); PG8_STAGE(PG8_SA(1, 0), a3, voffA);
;             PG8_BAR; PG8_WAIT_L(0); PG8_MMA(1, 0, At, B0); PG8_BAR; PG8_SCHED;
;             PG8_STAGE(PG8_SB(1, 1), b3 + hstep, voffB);
;             PG8_WAIT_V(6); PG8_BAR; PG8_MMA(1, 1, At, B1); PG8_BAR;
	s_waitcnt lgkmcnt(0)
	v_mfma_f32_16x16x32_bf16 v[64:67], v[202:205], v[148:151], v[64:67]
	v_mfma_f32_16x16x32_bf16 v[32:35], v[210:213], v[148:151], v[32:35]
	v_mfma_f32_16x16x32_bf16 v[60:63], v[202:205], v[156:159], v[60:63]
	v_mfma_f32_16x16x32_bf16 v[28:31], v[210:213], v[156:159], v[28:31]
	v_mfma_f32_16x16x32_bf16 v[56:59], v[202:205], v[172:175], v[56:59]
	v_mfma_f32_16x16x32_bf16 v[24:27], v[210:213], v[172:175], v[24:27]
	v_mfma_f32_16x16x32_bf16 v[52:55], v[202:205], v[194:197], v[52:55]
	v_mfma_f32_16x16x32_bf16 v[20:23], v[210:213], v[194:197], v[20:23]
	v_mfma_f32_16x16x32_bf16 v[64:67], v[206:209], v[152:155], v[64:67]
	v_mfma_f32_16x16x32_bf16 v[32:35], v[214:217], v[152:155], v[32:35]
	v_mfma_f32_16x16x32_bf16 v[60:63], v[206:209], v[168:171], v[60:63]
	v_mfma_f32_16x16x32_bf16 v[28:31], v[214:217], v[168:171], v[28:31]
	v_mfma_f32_16x16x32_bf16 v[56:59], v[206:209], v[190:193], v[56:59]
	v_mfma_f32_16x16x32_bf16 v[24:27], v[214:217], v[190:193], v[24:27]
	v_mfma_f32_16x16x32_bf16 v[52:55], v[206:209], v[198:201], v[52:55]
	v_mfma_f32_16x16x32_bf16 v[20:23], v[214:217], v[198:201], v[20:23]
	s_mov_b32 m0, s55
	v_lshl_add_u64 v[10:11], v[218:219], 0, s[86:87]
	s_barrier
	ds_read_b128 v[148:151], v249 offset:49152
	ds_read_b128 v[152:155], v249 offset:50176
	ds_read_b128 v[156:159], v249 offset:51200
	ds_read_b128 v[168:171], v249 offset:52224
	ds_read_b128 v[172:175], v249 offset:53248
	ds_read_b128 v[190:193], v249 offset:54272
	ds_read_b128 v[194:197], v249 offset:55296
	ds_read_b128 v[198:201], v249 offset:56320
	global_load_lds_dwordx4 v[10:11], off
	s_mov_b32 m0, s56
	v_lshl_add_u64 v[10:11], v[220:221], 0, s[86:87]
	global_load_lds_dwordx4 v[10:11], off
	s_barrier
	s_waitcnt lgkmcnt(0)
	v_mfma_f32_16x16x32_bf16 v[92:95], v[132:135], v[148:151], v[92:95]
	v_mfma_f32_16x16x32_bf16 v[84:87], v[140:143], v[148:151], v[84:87]
	v_mfma_f32_16x16x32_bf16 v[116:119], v[132:135], v[156:159], v[116:119]
	v_mfma_f32_16x16x32_bf16 v[76:79], v[140:143], v[156:159], v[76:79]
	v_mfma_f32_16x16x32_bf16 v[112:115], v[132:135], v[172:175], v[112:115]
	v_mfma_f32_16x16x32_bf16 v[72:75], v[140:143], v[172:175], v[72:75]
	v_mfma_f32_16x16x32_bf16 v[108:111], v[132:135], v[194:197], v[108:111]
	v_mfma_f32_16x16x32_bf16 v[68:71], v[140:143], v[194:197], v[68:71]
	v_mfma_f32_16x16x32_bf16 v[92:95], v[136:139], v[152:155], v[92:95]
	v_mfma_f32_16x16x32_bf16 v[84:87], v[144:147], v[152:155], v[84:87]
	v_mfma_f32_16x16x32_bf16 v[116:119], v[136:139], v[168:171], v[116:119]
	v_mfma_f32_16x16x32_bf16 v[76:79], v[144:147], v[168:171], v[76:79]
	v_mfma_f32_16x16x32_bf16 v[112:115], v[136:139], v[190:193], v[112:115]
	v_mfma_f32_16x16x32_bf16 v[72:75], v[144:147], v[190:193], v[72:75]
	v_mfma_f32_16x16x32_bf16 v[108:111], v[136:139], v[198:201], v[108:111]
	v_mfma_f32_16x16x32_bf16 v[68:71], v[144:147], v[198:201], v[68:71]
	s_barrier
	s_add_i32 s0, s0, s34
	s_mov_b32 m0, s0
	v_lshl_add_u64 v[10:11], v[222:223], 0, s[86:87]
	global_load_lds_dwordx4 v[10:11], off
	s_add_i32 m0, s0, 0x2000
	v_lshl_add_u64 v[10:11], v[224:225], 0, s[86:87]
	global_load_lds_dwordx4 v[10:11], off
	s_waitcnt vmcnt(6)
	s_barrier
	v_mfma_f32_16x16x32_bf16 v[48:51], v[202:205], v[148:151], v[48:51]
	v_mfma_f32_16x16x32_bf16 v[16:19], v[210:213], v[148:151], v[16:19]
	v_mfma_f32_16x16x32_bf16 v[44:47], v[202:205], v[156:159], v[44:47]
	v_mfma_f32_16x16x32_bf16 v[10:13], v[210:213], v[156:159], v[12:15]
	v_mfma_f32_16x16x32_bf16 v[40:43], v[202:205], v[172:175], v[40:43]
	v_mfma_f32_16x16x32_bf16 v[6:9], v[210:213], v[172:175], v[6:9]
	v_mfma_f32_16x16x32_bf16 v[36:39], v[202:205], v[194:197], v[36:39]
	v_mfma_f32_16x16x32_bf16 v[0:3], v[210:213], v[194:197], v[0:3]
	v_mfma_f32_16x16x32_bf16 v[48:51], v[206:209], v[152:155], v[48:51]
	v_mfma_f32_16x16x32_bf16 v[16:19], v[214:217], v[152:155], v[16:19]
	v_mfma_f32_16x16x32_bf16 v[44:47], v[206:209], v[168:171], v[44:47]
	v_mfma_f32_16x16x32_bf16 v[12:15], v[214:217], v[168:171], v[10:13]
	v_mfma_f32_16x16x32_bf16 v[40:43], v[206:209], v[190:193], v[40:43]
	v_mfma_f32_16x16x32_bf16 v[8:11], v[214:217], v[190:193], v[6:9]
	v_mfma_f32_16x16x32_bf16 v[36:39], v[206:209], v[198:201], v[36:39]
	v_mfma_f32_16x16x32_bf16 v[0:3], v[214:217], v[198:201], v[0:3]
	s_add_u32 s8, s8, 0x100
	s_addc_u32 s9, s9, 0
	s_add_u32 s62, s62, 0x100
	s_addc_u32 s63, s63, 0
	s_cmp_ge_u32 s64, s49
	s_mov_b32 s26, s64
	s_barrier
	s_cbranch_scc1 .Lpeel_exit_0
	.p2align 6
